# GEMM-phase prologues: second group of 6 LDS-DMA stages issued before the first wait (stagger barrier + B1 moved below them, vmcnt(2)->vmcnt(8)): first-tile latencies overlap
# baseline (speedup 1.0000x reference)
; __device__ __forceinline__ int my_tid() { int t = threadIdx.x; asm volatile("" : "+v"(t)); return t; }
; #define PG8_STAGE(bufoff, gbase, voff) do { _Pragma("unroll") for (int _i = 0; _i < 2; ++_i) \
;         __builtin_amdgcn_global_load_lds((const unsigned*)((const char*)(gbase) + (voff)[_i]), (LAS unsigned*)(lds + (bufoff) + ldsw + _i * 8192), 16, 0, 0); } while (0)
; #define PG8_BAR __builtin_amdgcn_s_barrier()
; template <class Epi, bool ALIGN_EPI>
; __device__ __forceinline__ void gemm_phase(LAS unsigned char* lds, const Gemm g, const StaticOrder& S, const Epi& E) {
;     const int tid = my_tid(), wid = __builtin_amdgcn_readfirstlane(tid >> 6), lane = tid & 63, wr = wid >> 2, wc = wid & 3, fr = lane & 15, fq = lane >> 4;
;     const int nt = g.K / BK;
;     unsigned voffA[2], voffB[2];
; #pragma unroll
;     for (int i = 0; i < 2; ++i) { int R, C; stage_rc(tid * 16 + i * 8192, R, C); const int Rb = Epi::PERM ? ((R & ~31) + perm32(R & 31)) : R;
;         voffA[i] = (unsigned)(R * g.lda + C) * 2u; voffB[i] = (unsigned)(Rb * g.ldb + C) * 2u; }
;     const size_t kstep = (size_t)(BK * 2);
;     const size_t hA = (size_t)HALF * g.lda * 2, hB = (size_t)HALF * g.ldb * 2;
;     const size_t tA = 2 * hA, tB = 2 * hB;
;     const unsigned ldsw = (unsigned)wid * 1024u;
;     const int aoff = lds_byte(wr * 64 + fr, fq * 8), boff = lds_byte(wc * 32 + fr, fq * 8);
;     ...
;     const char* cA = (const char*)g.A + (size_t)cur.pm * tA + (size_t)cur.pn * g.acol; const char* cB = (const char*)g.Bt + (size_t)cur.pn * tB;
;     PG8_STAGE(PG8_SB(0, 0), cB, voffB); PG8_STAGE(PG8_SB(0, 1), cB + hB, voffB); PG8_STAGE(PG8_SA(0, 0), cA, voffA); PG8_STAGE(PG8_SA(0, 1), cA + hA, voffA);
;     if (wr == 1) PG8_BAR;
.LBB0_238:
	s_cmp_lt_i32 s80, 2
	s_cselect_b64 s[10:11], -1, 0
	s_and_b64 s[0:1], s[10:11], s[4:5]
	s_andn2_b64 vcc, exec, s[0:1]
	s_cbranch_vccnz .LBB0_261
	s_mov_b64 s[4:5], s[78:79]
	v_mov_b32_e32 v0, v193
	v_mov_b32_e32 v8, v193
	s_cmpk_gt_i32 s84, 0x1ff
	s_nop 0
	v_readfirstlane_b32 s23, v8
	s_cbranch_scc1 .LBB0_261
	v_lshlrev_b32_e32 v0, 4, v8
	v_add_u32_e32 v1, 0x2000, v0
	v_ashrrev_i32_e32 v2, 31, v1
	v_lshrrev_b32_e32 v2, 22, v2
	v_add_u32_e32 v2, v1, v2
	s_waitcnt vmcnt(6)
	v_ashrrev_i32_e32 v9, 10, v2
	v_mul_i32_i24_e32 v2, 0x400, v9
	v_sub_u32_e32 v1, v1, v2
	v_lshrrev_b32_e32 v2, 4, v1
	v_bitop3_b32 v1, v2, v1, 32 bitop3:0x6c
	v_ashrrev_i32_e32 v2, 31, v1
	v_lshrrev_b32_e32 v2, 26, v2
	v_add_u32_e32 v2, v1, v2
	v_lshlrev_b32_e32 v3, 3, v9
	s_waitcnt vmcnt(4)
	v_ashrrev_i32_e32 v11, 6, v2
	v_and_b32_e32 v3, -16, v3
	v_add_u32_e32 v3, v11, v3
	v_and_b32_e32 v4, 3, v11
	s_mov_b32 s6, 0xfffe0
	v_lshrrev_b32_e32 v5, 2, v3
	v_lshlrev_b32_e32 v6, 1, v3
	v_and_b32_e32 v2, 0xc0, v2
	v_and_or_b32 v4, v3, s6, v4
	v_and_b32_e32 v5, 4, v5
	v_and_b32_e32 v6, 24, v6
	v_sub_u32_e32 v1, v1, v2
	v_mov_b32_e32 v2, 1
	v_or3_b32 v4, v4, v5, v6
	v_lshlrev_b32_e32 v5, 5, v9
	v_ashrrev_i16_sdwa v1, v2, sext(v1) dst_sel:DWORD dst_unused:UNUSED_PAD src0_sel:DWORD src1_sel:BYTE_0
	v_and_b32_e32 v5, 32, v5
	s_waitcnt vmcnt(3)
	v_bfe_i32 v12, v1, 0, 16
	v_add_lshl_u32 v1, v5, v12, 1
	v_lshl_add_u32 v128, v4, 12, v1
	v_lshl_add_u32 v130, v3, 12, v1
	v_bfe_i32 v1, v8, 27, 1
	v_lshrrev_b32_e32 v1, 22, v1
	v_add_u32_e32 v1, v0, v1
	v_and_b32_e32 v1, 0xfffffc00, v1
	v_sub_u32_e32 v0, v0, v1
	s_load_dwordx2 s[4:5], s[4:5], 0xe0
	v_lshrrev_b32_e32 v1, 4, v0
	v_bitop3_b32 v1, v1, v0, 32 bitop3:0x6c
	v_ashrrev_i32_e32 v0, 31, v0
	v_lshrrev_b32_e32 v0, 26, v0
	v_add_u32_e32 v0, v1, v0
	s_waitcnt vmcnt(2)
	v_ashrrev_i32_e32 v13, 6, v0
	v_ashrrev_i32_e32 v0, 31, v8
	s_waitcnt lgkmcnt(0)
	s_add_u32 s0, s4, 0x100000
	v_lshrrev_b32_e32 v0, 26, v0
	s_addc_u32 s1, s5, 0
	v_add_u32_e32 v0, v8, v0
	s_add_u32 s2, s4, 0xc000000
	s_waitcnt vmcnt(1)
	v_ashrrev_i32_e32 v14, 6, v0
	s_addc_u32 s3, s5, 0
	v_lshlrev_b32_e32 v0, 3, v14
	s_add_u32 s12, s4, 0x40000
	v_and_b32_e32 v0, -16, v0
	s_addc_u32 s13, s5, 0
	v_add_u32_e32 v0, v13, v0
	v_and_b32_e32 v3, 3, v13
	s_ashr_i32 s38, s84, 31
	v_and_or_b32 v3, v0, s6, v3
	s_lshr_b32 s6, s38, 29
	s_add_i32 s6, s84, s6
	s_and_b32 s7, s6, -8
	s_ashr_i32 s20, s23, 6
	s_ashr_i32 s21, s23, 8
	s_sub_i32 s7, s84, s7
	s_lshl_b32 s33, s20, 10
	s_lshl_b32 s24, s21, 6
	s_lshl_b32 s9, s7, 6
	s_ashr_i32 s6, s6, 3
	s_mul_i32 s8, s7, 0x41
	s_cmp_lt_i32 s7, 0
	s_cselect_b32 s7, s8, s9
	s_add_i32 s6, s7, s6
	s_ashr_i32 s7, s6, 31
	s_lshr_b32 s7, s7, 27
	s_add_i32 s7, s6, s7
	s_ashr_i32 s8, s7, 5
	s_andn2_b32 s7, s7, 31
	s_sub_i32 s6, s6, s7
	s_bfe_i32 s7, s6, 0x80000
	s_bfe_u32 s7, s7, 0x2000d
	v_lshrrev_b32_e32 v4, 2, v0
	v_lshlrev_b32_e32 v5, 1, v0
	s_add_i32 s7, s6, s7
	v_and_b32_e32 v4, 4, v4
	v_and_b32_e32 v5, 24, v5
	s_bfe_i32 s9, s7, 0x80000
	s_and_b32 s7, s7, 0xfc
	v_or3_b32 v3, v3, v4, v5
	v_mul_i32_i24_e32 v5, 64, v13
	s_sub_i32 s6, s6, s7
	v_sub_u32_e32 v1, v1, v5
	s_lshl_b32 s8, s8, 2
	s_sext_i32_i8 s6, s6
	v_lshlrev_b32_e32 v4, 5, v14
	v_ashrrev_i16_sdwa v1, v2, sext(v1) dst_sel:DWORD dst_unused:UNUSED_PAD src0_sel:DWORD src1_sel:BYTE_0
	s_sext_i32_i16 s9, s9
	s_add_i32 s52, s8, s6
	v_and_b32_e32 v4, 32, v4
	s_waitcnt vmcnt(0)
	v_bfe_i32 v15, v1, 0, 16
	s_lshr_b32 s22, s9, 2
	s_lshl_b32 s6, s52, 8
	v_and_b32_e32 v10, 15, v8
	v_add_lshl_u32 v1, v4, v15, 1
	s_add_i32 s6, s6, s24
	s_ashr_i32 s53, s52, 31
	s_bfe_i64 s[8:9], s[22:23], 0x100000
	v_lshl_add_u32 v134, v0, 12, v1
	v_or_b32_e32 v0, s6, v10
	s_lshl_b64 s[6:7], s[52:53], 20
	s_lshl_b64 s[8:9], s[8:9], 20
	s_add_u32 s8, s0, s8
	v_lshl_add_u32 v132, v3, 12, v1
	v_ashrrev_i32_e32 v1, 31, v0
	s_addc_u32 s9, s1, s9
	s_add_i32 s39, s33, 0
	v_lshl_add_u64 v[0:1], v[0:1], 2, s[12:13]
	s_add_i32 m0, s39, 0x10000
	global_load_dword v166, v[0:1], off
	global_load_dword v165, v[0:1], off offset:64
	global_load_dword v152, v[0:1], off offset:128
	global_load_dword v150, v[0:1], off offset:192
	global_load_dword v148, v[0:1], off offset:512
	global_load_dword v146, v[0:1], off offset:576
	global_load_dword v145, v[0:1], off offset:640
	global_load_dword v144, v[0:1], off offset:704
	v_mov_b32_e32 v133, 0
	global_load_lds_dwordx4 v132, s[8:9]
	s_add_i32 m0, s39, 0x12000
	s_add_u32 s14, s8, 0x80000
	global_load_lds_dwordx4 v128, s[8:9]
	s_addc_u32 s15, s9, 0
	s_add_i32 m0, s39, 0x14000
	v_mov_b32_e32 v129, v133
	global_load_lds_dwordx4 v132, s[14:15]
	s_add_i32 m0, s39, 0x16000
	s_add_u32 s6, s2, s6
	s_addc_u32 s7, s3, s7
	s_add_i32 s53, s39, 0x2000
	global_load_lds_dwordx4 v128, s[14:15]
	s_mov_b32 m0, s39
	s_add_u32 s14, s6, 0x80000
	global_load_lds_dwordx4 v134, s[6:7]
	s_mov_b32 m0, s53
	s_addc_u32 s15, s7, 0
	s_add_i32 s56, s39, 0x4000
	global_load_lds_dwordx4 v130, s[6:7]
	s_mov_b32 m0, s56
	s_add_i32 s57, s39, 0x6000
	global_load_lds_dwordx4 v134, s[14:15]
	s_mov_b32 m0, s57
	v_mov_b32_e32 v135, v133
	global_load_lds_dwordx4 v130, s[14:15]
	v_mov_b32_e32 v131, v133
	s_cmp_eq_u32 s21, 1
	s_mov_b32 s58, 0
	v_lshl_add_u64 v[6:7], s[8:9], 0, v[132:133]
	v_lshl_add_u64 v[2:3], s[8:9], 0, v[128:129]
	s_mov_b64 s[14:15], 0x80000
	v_lshl_add_u64 v[0:1], s[6:7], 0, v[134:135]
	s_cselect_b64 s[16:17], -1, 0
	s_cmp_lg_u32 s21, 1
	v_lshl_add_u64 v[4:5], s[6:7], 0, v[130:131]
	s_cbranch_scc1 .LBB0_242
	s_nop 0
; #define PG8_STAGE(bufoff, gbase, voff) do { _Pragma("unroll") for (int _i = 0; _i < 2; ++_i) \
;         __builtin_amdgcn_global_load_lds((const unsigned*)((const char*)(gbase) + (voff)[_i]), (LAS unsigned*)(lds + (bufoff) + ldsw + _i * 8192), 16, 0, 0); } while (0)
; #define PG8_WAIT_V(n) asm volatile("s_waitcnt vmcnt(" #n ")" ::: "memory")
; #define PG8_BAR __builtin_amdgcn_s_barrier()
; template <class Epi, bool ALIGN_EPI>
; __device__ __forceinline__ void gemm_phase(LAS unsigned char* lds, const Gemm g, const StaticOrder& S, const Epi& E) {
;     ...
;     PG8_STAGE(PG8_SB(1, 0), cB + kstep, voffB); PG8_STAGE(PG8_SA(1, 0), cA + kstep, voffA); PG8_STAGE(PG8_SB(1, 1), cB + hB + kstep, voffB);
;     PG8_WAIT_V(6); PG8_BAR;
.LBB0_242:
	s_ashr_i32 s59, s76, 31
	s_add_u32 s18, s4, 0x10000000
	s_addc_u32 s19, s5, 0
	s_lshl_b32 s25, s21, 13
	s_lshl_b32 s4, s20, 5
	s_mov_b64 s[20:21], 0x80
	s_and_b32 s26, s4, 0x60
	s_add_i32 m0, s39, 0x18000
	v_lshl_add_u64 v[6:7], v[6:7], 0, s[20:21]
	s_lshl_b32 s27, s26, 7
	global_load_lds_dwordx4 v[6:7], off
	v_lshl_add_u64 v[2:3], v[2:3], 0, s[20:21]
	s_add_i32 m0, s39, 0x1a000
	s_add_i32 s60, s39, 0x8000
	s_add_i32 s61, s39, 0xa000
	global_load_lds_dwordx4 v[2:3], off
	v_lshl_add_u64 v[0:1], v[0:1], 0, s[20:21]
	s_mov_b32 m0, s60
	s_add_u32 s4, s8, 0x80080
	global_load_lds_dwordx4 v[0:1], off
	v_lshl_add_u64 v[0:1], v[4:5], 0, s[20:21]
	s_mov_b32 m0, s61
	s_addc_u32 s5, s9, 0
	global_load_lds_dwordx4 v[0:1], off
	s_add_i32 m0, s39, 0x1c000
	v_lshl_add_u64 v[0:1], s[4:5], 0, v[132:133]
	global_load_lds_dwordx4 v[0:1], off
	v_lshl_add_u64 v[0:1], s[4:5], 0, v[128:129]
	s_add_i32 m0, s39, 0x1e000
	v_or_b32_e32 v147, s24, v10
	global_load_lds_dwordx4 v[0:1], off
	s_cselect_b32 s97, 1, 0
	v_readfirstlane_b32 s101, v193
	s_nop 3
	s_lshr_b32 s101, s101, 6
	s_cmp_lt_u32 s101, 4
	s_cbranch_scc1 .Lpro_skip_1
	s_barrier
.Lpro_skip_1:
	s_waitcnt vmcnt(8)
	s_barrier
	s_cmp_lg_u32 s97, 0
	v_lshrrev_b32_e32 v0, 1, v8
	v_and_b32_e32 v0, 24, v0
	v_lshlrev_b32_e32 v1, 6, v147
	v_lshlrev_b32_e32 v2, 1, v0
	s_movk_i32 s4, 0x3c0
	v_lshlrev_b32_e32 v3, 2, v147
	v_and_or_b32 v1, v1, s4, v2
	v_and_b32_e32 v3, 32, v3
	v_bitop3_b32 v1, v1, s25, v3 bitop3:0xde
	v_lshlrev_b32_e32 v3, 2, v10
	v_or_b32_e32 v151, s26, v0
	v_lshlrev_b32_e32 v0, 15, v14
	v_lshl_or_b32 v2, v10, 6, v2
	v_and_b32_e32 v3, 32, v3
	v_and_b32_e32 v0, 0xffff0000, v0
	v_bitop3_b32 v149, v2, s27, v3 bitop3:0xde
	v_lshl_add_u32 v0, v13, 12, v0
	v_and_b32_e32 v2, 1, v14
	v_lshl_or_b32 v0, v2, 6, v0
	v_lshl_add_u32 v136, v15, 1, v0
	v_lshlrev_b32_e32 v0, 15, v9
	v_and_b32_e32 v0, 0xffff0000, v0
	s_waitcnt vmcnt(6)
	s_cmpk_lt_u32 s23, 0x100
	v_lshl_add_u32 v0, v11, 12, v0
	v_and_b32_e32 v2, 1, v9
	s_sext_i32_i8 s66, s22
	s_cselect_b64 s[22:23], -1, 0
	v_lshl_or_b32 v0, v2, 6, v0
	s_add_i32 s63, 0, 0x10000
	s_add_i32 s64, 0, 0x14000
	s_mov_b32 s62, s76
	v_mov_b32_e32 v137, v133
	v_lshl_add_u32 v138, v12, 1, v0
	v_mov_b32_e32 v139, v133
	v_mov_b64_e32 v[140:141], 0x200
	v_mov_b64_e32 v[142:143], 0x1ff
	s_mov_b64 s[24:25], 0x100
	v_add_u32_e32 v153, s63, v149
	v_add_u32_e32 v154, s64, v149
	v_add_u32_e32 v155, 0, v1
	v_mov_b32_e32 v156, 0x358637bd
	s_mov_b32 s65, 0x800000
	s_mov_b64 s[26:27], 0x80100
	s_mov_b64 s[28:29], 0x90000
	s_mov_b64 s[30:31], 0x90100
	s_mov_b64 s[34:35], 0xa0000
	s_mov_b64 s[36:37], 0xa0100
	s_mov_b64 s[40:41], 0xb0000
	s_mov_b64 s[42:43], 0xb0100
	s_barrier
	s_branch .LBB0_245

; __device__ __forceinline__ int my_tid() { int t = threadIdx.x; asm volatile("" : "+v"(t)); return t; }
; #define PG8_STAGE(bufoff, gbase, voff) do { _Pragma("unroll") for (int _i = 0; _i < 2; ++_i) \
;         __builtin_amdgcn_global_load_lds((const unsigned*)((const char*)(gbase) + (voff)[_i]), (LAS unsigned*)(lds + (bufoff) + ldsw + _i * 8192), 16, 0, 0); } while (0)
; #define PG8_BAR __builtin_amdgcn_s_barrier()
; template <class Epi, bool ALIGN_EPI>
; __device__ __forceinline__ void gemm_phase(LAS unsigned char* lds, const Gemm g, const StaticOrder& S, const Epi& E) {
;     const int tid = my_tid(), wid = __builtin_amdgcn_readfirstlane(tid >> 6), lane = tid & 63, wr = wid >> 2, wc = wid & 3, fr = lane & 15, fq = lane >> 4;
;     const int nt = g.K / BK;
;     unsigned voffA[2], voffB[2];
; #pragma unroll
;     for (int i = 0; i < 2; ++i) { int R, C; stage_rc(tid * 16 + i * 8192, R, C); const int Rb = Epi::PERM ? ((R & ~31) + perm32(R & 31)) : R;
;         voffA[i] = (unsigned)(R * g.lda + C) * 2u; voffB[i] = (unsigned)(Rb * g.ldb + C) * 2u; }
;     const size_t kstep = (size_t)(BK * 2);
;     const size_t hA = (size_t)HALF * g.lda * 2, hB = (size_t)HALF * g.ldb * 2;
;     const size_t tA = 2 * hA, tB = 2 * hB;
;     const unsigned ldsw = (unsigned)wid * 1024u;
;     const int aoff = lds_byte(wr * 64 + fr, fq * 8), boff = lds_byte(wc * 32 + fr, fq * 8);
;     ...
;     const char* cA = (const char*)g.A + (size_t)cur.pm * tA + (size_t)cur.pn * g.acol; const char* cB = (const char*)g.Bt + (size_t)cur.pn * tB;
;     PG8_STAGE(PG8_SB(0, 0), cB, voffB); PG8_STAGE(PG8_SB(0, 1), cB + hB, voffB); PG8_STAGE(PG8_SA(0, 0), cA, voffA); PG8_STAGE(PG8_SA(0, 1), cA + hA, voffA);
;     if (wr == 1) PG8_BAR;
.LBB0_375:
	s_cmp_lt_i32 s80, 4
	s_cselect_b64 s[12:13], -1, 0
	s_and_b64 s[0:1], s[12:13], s[4:5]
	s_andn2_b64 vcc, exec, s[0:1]
	s_cbranch_vccnz .LBB0_426
	s_ashr_i32 s44, s84, 31
	s_lshr_b32 s0, s44, 29
	s_mov_b64 s[2:3], s[78:79]
	v_mov_b32_e32 v0, v193
	s_add_i32 s1, s84, s0
	s_load_dwordx4 s[8:11], s[2:3], 0xd8
	s_ashr_i32 s0, s1, 3
	s_and_b32 s1, s1, -8
	s_waitcnt lgkmcnt(0)
	s_ashr_i32 s33, s76, 31
	s_sub_i32 s1, s84, s1
	s_cmp_lt_i32 s1, 0
	s_waitcnt vmcnt(6)
	v_mov_b32_e32 v9, v193
	s_cselect_b64 s[6:7], -1, 0
	s_cmpk_gt_i32 s84, 0x2ff
	s_nop 0
	v_readfirstlane_b32 s5, v9
	s_cbranch_scc1 .LBB0_392
	v_lshlrev_b32_e32 v0, 4, v9
	v_add_u32_e32 v1, 0x2000, v0
	v_ashrrev_i32_e32 v2, 31, v1
	v_lshrrev_b32_e32 v2, 22, v2
	v_add_u32_e32 v2, v1, v2
	v_ashrrev_i32_e32 v8, 10, v2
	v_mul_i32_i24_e32 v2, 0x400, v8
	v_sub_u32_e32 v1, v1, v2
	v_lshrrev_b32_e32 v2, 4, v1
	v_bitop3_b32 v1, v2, v1, 32 bitop3:0x6c
	v_ashrrev_i32_e32 v2, 31, v1
	v_lshrrev_b32_e32 v2, 26, v2
	v_add_u32_e32 v2, v1, v2
	v_lshlrev_b32_e32 v3, 3, v8
	s_waitcnt vmcnt(5)
	v_ashrrev_i32_e32 v10, 6, v2
	v_and_b32_e32 v3, -16, v3
	v_add_u32_e32 v3, v10, v3
	v_and_b32_e32 v4, 3, v10
	s_mov_b32 s4, 0x3fffe0
	v_lshrrev_b32_e32 v5, 2, v3
	v_lshlrev_b32_e32 v6, 1, v3
	v_and_b32_e32 v2, 0xc0, v2
	v_and_or_b32 v4, v3, s4, v4
	v_and_b32_e32 v5, 4, v5
	v_and_b32_e32 v6, 24, v6
	v_sub_u32_e32 v1, v1, v2
	v_mov_b32_e32 v2, 1
	v_or3_b32 v4, v4, v5, v6
	v_lshlrev_b32_e32 v5, 5, v8
	v_ashrrev_i16_sdwa v1, v2, sext(v1) dst_sel:DWORD dst_unused:UNUSED_PAD src0_sel:DWORD src1_sel:BYTE_0
	v_and_b32_e32 v5, 32, v5
	s_waitcnt vmcnt(4)
	v_bfe_i32 v11, v1, 0, 16
	v_add_lshl_u32 v1, v5, v11, 1
	v_lshl_add_u32 v128, v4, 10, v1
	v_lshl_add_u32 v130, v3, 12, v1
	v_bfe_i32 v1, v9, 27, 1
	v_lshrrev_b32_e32 v1, 22, v1
	v_add_u32_e32 v1, v0, v1
	v_and_b32_e32 v1, 0xfffffc00, v1
	v_sub_u32_e32 v0, v0, v1
	v_lshrrev_b32_e32 v1, 4, v0
	v_bitop3_b32 v1, v1, v0, 32 bitop3:0x6c
	v_ashrrev_i32_e32 v0, 31, v0
	v_lshrrev_b32_e32 v0, 26, v0
	v_add_u32_e32 v0, v1, v0
	s_waitcnt vmcnt(3)
	v_ashrrev_i32_e32 v12, 6, v0
	v_ashrrev_i32_e32 v0, 31, v9
	s_add_u32 s2, s10, 0xc60000
	v_lshrrev_b32_e32 v0, 26, v0
	s_addc_u32 s3, s11, 0
	v_add_u32_e32 v0, v9, v0
	s_add_u32 s38, s10, 0x10000600
	s_waitcnt vmcnt(2)
	v_ashrrev_i32_e32 v13, 6, v0
	s_addc_u32 s39, s11, 0
	s_ashr_i32 s18, s5, 6
	v_lshlrev_b32_e32 v0, 3, v13
	s_ashr_i32 s20, s5, 8
	s_lshl_b32 s45, s18, 10
	v_and_b32_e32 v0, -16, v0
	v_add_u32_e32 v0, v12, v0
	v_and_b32_e32 v3, 3, v12
	s_movk_i32 s46, 0x61
	s_and_b64 s[14:15], s[6:7], exec
	v_and_or_b32 v3, v0, s4, v3
	s_cselect_b32 s4, s46, 0x60
	s_mul_i32 s4, s1, s4
	s_add_i32 s4, s4, s0
	s_mul_hi_i32 s14, s4, 0x2aaaaaab
	s_lshr_b32 s15, s14, 31
	s_ashr_i32 s14, s14, 3
	s_add_i32 s14, s14, s15
	s_lshl_b32 s15, s14, 2
	s_mul_i32 s14, s14, 48
	s_sub_i32 s14, s4, s14
	s_bfe_i32 s4, s14, 0x80000
	s_bfe_u32 s4, s4, 0x2000d
	s_add_i32 s16, s14, s4
	s_bfe_i32 s4, s16, 0x80000
	s_and_b32 s16, s16, 0xfc
	v_lshrrev_b32_e32 v4, 2, v0
	v_lshlrev_b32_e32 v5, 1, v0
	s_sub_i32 s14, s14, s16
	v_and_b32_e32 v4, 4, v4
	v_and_b32_e32 v5, 24, v5
	s_sext_i32_i16 s4, s4
	s_sext_i32_i8 s14, s14
	v_or3_b32 v3, v3, v4, v5
	v_mul_i32_i24_e32 v5, 64, v12
	s_lshr_b32 s4, s4, 2
	s_add_i32 s34, s15, s14
	v_sub_u32_e32 v1, v1, v5
	s_ashr_i32 s35, s34, 31
	s_bfe_i64 s[16:17], s[4:5], 0x100000
	v_lshlrev_b32_e32 v4, 5, v13
	v_ashrrev_i16_sdwa v1, v2, sext(v1) dst_sel:DWORD dst_unused:UNUSED_PAD src0_sel:DWORD src1_sel:BYTE_0
	s_lshl_b64 s[14:15], s[34:35], 20
	s_lshl_b64 s[16:17], s[16:17], 18
	v_and_b32_e32 v4, 32, v4
	s_waitcnt vmcnt(1)
	v_bfe_i32 v14, v1, 0, 16
	s_add_u32 s40, s2, s16
	v_add_lshl_u32 v1, v4, v14, 1
	s_addc_u32 s41, s3, s17
	s_add_i32 s35, s45, 0
	v_lshl_add_u32 v132, v3, 10, v1
	s_add_i32 m0, s35, 0x10000
	v_lshl_add_u32 v134, v0, 12, v1
	global_load_lds_dwordx4 v132, s[40:41]
	s_add_i32 m0, s35, 0x12000
	s_add_u32 s16, s40, 0x20000
	global_load_lds_dwordx4 v128, s[40:41]
	s_addc_u32 s17, s41, 0
	s_add_i32 m0, s35, 0x14000
	v_mov_b32_e32 v133, 0
	global_load_lds_dwordx4 v132, s[16:17]
	s_add_i32 m0, s35, 0x16000
	s_add_u32 s36, s38, s14
	s_addc_u32 s37, s39, s15
	s_add_i32 s47, s35, 0x2000
	global_load_lds_dwordx4 v128, s[16:17]
	s_mov_b32 m0, s35
	s_add_u32 s14, s36, 0x80000
	global_load_lds_dwordx4 v134, s[36:37]
	s_mov_b32 m0, s47
	s_addc_u32 s15, s37, 0
	s_add_i32 s48, s35, 0x4000
	global_load_lds_dwordx4 v130, s[36:37]
	s_mov_b32 m0, s48
	s_add_i32 s49, s35, 0x6000
	global_load_lds_dwordx4 v134, s[14:15]
	s_mov_b32 m0, s49
	v_mov_b32_e32 v129, v133
	global_load_lds_dwordx4 v130, s[14:15]
	v_mov_b32_e32 v135, v133
	v_mov_b32_e32 v131, v133
	s_cmp_eq_u32 s20, 1
	v_lshl_add_u64 v[6:7], s[40:41], 0, v[132:133]
	v_lshl_add_u64 v[4:5], s[40:41], 0, v[128:129]
	v_lshl_add_u64 v[0:1], s[36:37], 0, v[134:135]
	s_cselect_b64 s[14:15], -1, 0
	s_cmp_lg_u32 s20, 1
	v_lshl_add_u64 v[2:3], s[36:37], 0, v[130:131]
	s_cbranch_scc1 .LBB0_379
	s_nop 0
; #define PG8_STAGE(bufoff, gbase, voff) do { _Pragma("unroll") for (int _i = 0; _i < 2; ++_i) \
;         __builtin_amdgcn_global_load_lds((const unsigned*)((const char*)(gbase) + (voff)[_i]), (LAS unsigned*)(lds + (bufoff) + ldsw + _i * 8192), 16, 0, 0); } while (0)
; #define PG8_WAIT_V(n) asm volatile("s_waitcnt vmcnt(" #n ")" ::: "memory")
; #define PG8_BAR __builtin_amdgcn_s_barrier()
; template <class Epi, bool ALIGN_EPI>
; __device__ __forceinline__ void gemm_phase(LAS unsigned char* lds, const Gemm g, const StaticOrder& S, const Epi& E) {
;     ...
;     PG8_STAGE(PG8_SB(1, 0), cB + kstep, voffB); PG8_STAGE(PG8_SA(1, 0), cA + kstep, voffA); PG8_STAGE(PG8_SB(1, 1), cB + hB + kstep, voffB);
;     PG8_WAIT_V(6); PG8_BAR;
.LBB0_379:
	s_add_u32 s16, s10, 0x14000000
	s_addc_u32 s17, s11, 0
	s_lshl_b32 s18, s18, 5
	s_and_b32 s24, s18, 0x60
	s_mov_b64 s[18:19], 0x80
	s_add_i32 m0, s35, 0x18000
	v_lshl_add_u64 v[6:7], v[6:7], 0, s[18:19]
	s_lshl_b32 s21, s20, 13
	s_lshl_b32 s25, s24, 7
	global_load_lds_dwordx4 v[6:7], off
	v_lshl_add_u64 v[4:5], v[4:5], 0, s[18:19]
	s_add_i32 m0, s35, 0x1a000
	s_add_i32 s50, s35, 0x8000
	s_add_i32 s51, s35, 0xa000
	global_load_lds_dwordx4 v[4:5], off
	v_lshl_add_u64 v[0:1], v[0:1], 0, s[18:19]
	s_mov_b32 m0, s50
	s_add_u32 s22, s40, 0x20080
	global_load_lds_dwordx4 v[0:1], off
	v_lshl_add_u64 v[0:1], v[2:3], 0, s[18:19]
	s_mov_b32 m0, s51
	s_addc_u32 s23, s41, 0
	global_load_lds_dwordx4 v[0:1], off
	s_add_i32 m0, s35, 0x1c000
	v_lshl_add_u64 v[0:1], s[22:23], 0, v[132:133]
	global_load_lds_dwordx4 v[0:1], off
	v_lshl_add_u64 v[0:1], s[22:23], 0, v[128:129]
	s_add_i32 m0, s35, 0x1e000
	s_cmpk_lt_u32 s5, 0x100
	global_load_lds_dwordx4 v[0:1], off
	s_cselect_b32 s97, 1, 0
	v_readfirstlane_b32 s101, v193
	s_nop 3
	s_lshr_b32 s101, s101, 6
	s_cmp_lt_u32 s101, 4
	s_cbranch_scc1 .Lpro_skip_2
	s_barrier
.Lpro_skip_2:
	s_waitcnt vmcnt(8)
	s_barrier
	s_cmp_lg_u32 s97, 0
	v_lshrrev_b32_e32 v1, 1, v9
	v_and_b32_e32 v1, 24, v1
	v_and_b32_e32 v0, 15, v9
	v_lshlrev_b32_e32 v2, 1, v1
	v_lshl_or_b32 v146, s20, 6, v0
	v_lshl_or_b32 v0, v0, 6, v2
	v_lshlrev_b32_e32 v2, 2, v9
	v_and_b32_e32 v2, 32, v2
	v_bitop3_b32 v3, v0, s21, v2 bitop3:0xde
	v_bitop3_b32 v147, v0, s25, v2 bitop3:0xde
	v_lshlrev_b32_e32 v0, 15, v13
	v_and_b32_e32 v0, 0xffff0000, v0
	v_or_b32_e32 v148, s24, v1
	v_lshl_add_u32 v0, v12, 12, v0
	v_and_b32_e32 v1, 1, v13
	v_lshl_or_b32 v0, v1, 6, v0
	v_lshl_add_u32 v136, v14, 1, v0
	v_lshlrev_b32_e32 v0, 15, v8
	v_and_b32_e32 v0, 0xffff0000, v0
	s_waitcnt vmcnt(6)
	v_lshl_add_u32 v0, v10, 12, v0
	v_and_b32_e32 v1, 1, v8
	s_cselect_b64 s[20:21], -1, 0
	v_lshl_or_b32 v0, v1, 6, v0
	s_add_i32 s53, 0, 0x10000
	s_add_i32 s54, 0, 0x14000
	s_sext_i32_i8 s56, s4
	s_mov_b32 s52, 0
	v_mov_b32_e32 v137, v133
	v_lshl_add_u32 v138, v11, 1, v0
	v_mov_b32_e32 v139, v133
	v_mov_b64_e32 v[140:141], 0x300
	v_mov_b64_e32 v[142:143], 0x2ff
	s_mov_b64 s[22:23], 0x100
	v_add_u32_e32 v149, s53, v147
	v_add_u32_e32 v150, s54, v147
	v_add_u32_e32 v151, 0, v3
	s_movk_i32 s55, 0x1800
	s_barrier
	s_waitcnt vmcnt(0)
	s_branch .LBB0_382

; __device__ __forceinline__ int my_tid() { int t = threadIdx.x; asm volatile("" : "+v"(t)); return t; }
; #define PG8_STAGE(bufoff, gbase, voff) do { _Pragma("unroll") for (int _i = 0; _i < 2; ++_i) \
;         __builtin_amdgcn_global_load_lds((const unsigned*)((const char*)(gbase) + (voff)[_i]), (LAS unsigned*)(lds + (bufoff) + ldsw + _i * 8192), 16, 0, 0); } while (0)
; #define PG8_WAIT_V(n) asm volatile("s_waitcnt vmcnt(" #n ")" ::: "memory")
; #define PG8_BAR __builtin_amdgcn_s_barrier()
; template <class Epi, bool ALIGN_EPI>
; __device__ __forceinline__ void gemm_phase(LAS unsigned char* lds, const Gemm g, const StaticOrder& S, const Epi& E) {
;     const int tid = my_tid(), wid = __builtin_amdgcn_readfirstlane(tid >> 6), lane = tid & 63, wr = wid >> 2, wc = wid & 3, fr = lane & 15, fq = lane >> 4;
;     const int nt = g.K / BK;
;     unsigned voffA[2], voffB[2];
; #pragma unroll
;     for (int i = 0; i < 2; ++i) { int R, C; stage_rc(tid * 16 + i * 8192, R, C); const int Rb = Epi::PERM ? ((R & ~31) + perm32(R & 31)) : R;
;         voffA[i] = (unsigned)(R * g.lda + C) * 2u; voffB[i] = (unsigned)(Rb * g.ldb + C) * 2u; }
;     const size_t kstep = (size_t)(BK * 2);
;     const size_t hA = (size_t)HALF * g.lda * 2, hB = (size_t)HALF * g.ldb * 2;
;     const size_t tA = 2 * hA, tB = 2 * hB;
;     const unsigned ldsw = (unsigned)wid * 1024u;
;     const int aoff = lds_byte(wr * 64 + fr, fq * 8), boff = lds_byte(wc * 32 + fr, fq * 8);
;     ...
;     const char* cA = (const char*)g.A + (size_t)cur.pm * tA + (size_t)cur.pn * g.acol; const char* cB = (const char*)g.Bt + (size_t)cur.pn * tB;
;     PG8_STAGE(PG8_SB(0, 0), cB, voffB); PG8_STAGE(PG8_SB(0, 1), cB + hB, voffB); PG8_STAGE(PG8_SA(0, 0), cA, voffA); PG8_STAGE(PG8_SA(0, 1), cA + hA, voffA);
;     if (wr == 1) PG8_BAR;
;     PG8_WAIT_V(2); PG8_BAR;
;     PG8_STAGE(PG8_SB(1, 0), cB + kstep, voffB); PG8_STAGE(PG8_SA(1, 0), cA + kstep, voffA); PG8_STAGE(PG8_SB(1, 1), cB + hB + kstep, voffB);
;     PG8_WAIT_V(6); PG8_BAR;
.Lq_remap_done:
	v_lshlrev_b32_e32 v0, 4, v9
	v_add_u32_e32 v1, 0x2000, v0
	v_ashrrev_i32_e32 v2, 31, v1
	v_lshrrev_b32_e32 v2, 22, v2
	v_add_u32_e32 v2, v1, v2
	v_ashrrev_i32_e32 v8, 10, v2
	v_mul_i32_i24_e32 v2, 0x400, v8
	v_sub_u32_e32 v1, v1, v2
	v_lshrrev_b32_e32 v2, 4, v1
	v_bitop3_b32 v1, v2, v1, 32 bitop3:0x6c
	v_ashrrev_i32_e32 v2, 31, v1
	v_lshrrev_b32_e32 v2, 26, v2
	v_add_u32_e32 v2, v1, v2
	v_lshlrev_b32_e32 v3, 3, v8
	s_waitcnt vmcnt(0)
	v_ashrrev_i32_e32 v10, 6, v2
	v_and_b32_e32 v3, -16, v3
	v_add_u32_e32 v3, v10, v3
	v_and_b32_e32 v4, 3, v10
	s_mov_b32 s14, 0xffffe0
	v_lshrrev_b32_e32 v5, 2, v3
	v_lshlrev_b32_e32 v6, 1, v3
	v_and_b32_e32 v2, 0xc0, v2
	v_and_or_b32 v4, v3, s14, v4
	v_and_b32_e32 v5, 4, v5
	v_and_b32_e32 v6, 24, v6
	v_sub_u32_e32 v1, v1, v2
	v_mov_b32_e32 v2, 1
	s_ashr_i32 s16, s4, 6
	v_or3_b32 v4, v4, v5, v6
	v_lshlrev_b32_e32 v5, 5, v8
	v_ashrrev_i16_sdwa v1, v2, sext(v1) dst_sel:DWORD dst_unused:UNUSED_PAD src0_sel:DWORD src1_sel:BYTE_0
	s_ashr_i32 s5, s4, 8
	s_lshl_b32 s2, s16, 10
	v_and_b32_e32 v5, 32, v5
	v_bfe_i32 v11, v1, 0, 16
	s_add_u32 s3, s10, 0x900000
	v_mul_u32_u24_e32 v4, 0x300, v4
	v_add_u32_e32 v1, v5, v11
	v_lshlrev_b32_e32 v3, 12, v3
	s_addc_u32 s36, s11, 0
	v_add_lshl_u32 v128, v4, v1, 1
	v_lshl_add_u32 v130, v1, 1, v3
	v_bfe_i32 v1, v9, 27, 1
	s_add_u32 s37, s10, 0x10000000
	v_lshrrev_b32_e32 v1, 22, v1
	s_addc_u32 s38, s11, 0
	v_add_u32_e32 v1, v0, v1
	v_and_b32_e32 v1, 0xfffffc00, v1
	s_movk_i32 s39, 0x49
	s_and_b64 s[6:7], s[6:7], exec
	v_sub_u32_e32 v0, v0, v1
	s_cselect_b32 s6, s39, 0x48
	v_lshrrev_b32_e32 v1, 4, v0
	s_mul_i32 s1, s1, s6
	v_bitop3_b32 v1, v1, v0, 32 bitop3:0x6c
	v_ashrrev_i32_e32 v0, 31, v0
	s_add_i32 s1, s1, s0
	v_lshrrev_b32_e32 v0, 26, v0
	s_mul_hi_i32 s0, s1, 0x38e38e39
	v_add_u32_e32 v0, v1, v0
	s_lshr_b32 s6, s0, 31
	s_ashr_i32 s0, s0, 3
	v_ashrrev_i32_e32 v12, 6, v0
	v_ashrrev_i32_e32 v0, 31, v9
	s_add_i32 s0, s0, s6
	v_lshrrev_b32_e32 v0, 26, v0
	s_lshl_b32 s7, s0, 2
	s_mul_i32 s0, s0, 36
	v_add_u32_e32 v0, v9, v0
	s_sub_i32 s0, s1, s0
	v_ashrrev_i32_e32 v13, 6, v0
	s_bfe_i32 s1, s0, 0x80000
	v_lshlrev_b32_e32 v0, 3, v13
	s_bfe_u32 s1, s1, 0x2000d
	v_and_b32_e32 v0, -16, v0
	s_add_i32 s1, s0, s1
	v_add_u32_e32 v0, v12, v0
	s_bfe_i32 s6, s1, 0x80000
	s_and_b32 s1, s1, 0xfc
	v_and_b32_e32 v3, 3, v12
	v_lshrrev_b32_e32 v4, 2, v0
	v_lshlrev_b32_e32 v5, 1, v0
	s_sub_i32 s0, s0, s1
	v_and_or_b32 v3, v0, s14, v3
	v_and_b32_e32 v4, 4, v4
	v_and_b32_e32 v5, 24, v5
	s_sext_i32_i8 s0, s0
	v_or3_b32 v3, v3, v4, v5
	v_mul_i32_i24_e32 v5, 64, v12
	s_sext_i32_i16 s17, s6
	s_add_i32 s28, s7, s0
	v_sub_u32_e32 v1, v1, v5
	s_ashr_i32 s29, s28, 31
	s_ashr_i32 s0, s17, 2
	v_lshlrev_b32_e32 v4, 5, v13
	v_ashrrev_i16_sdwa v1, v2, sext(v1) dst_sel:DWORD dst_unused:UNUSED_PAD src0_sel:DWORD src1_sel:BYTE_0
	s_lshr_b32 s6, s17, 2
	s_lshl_b64 s[14:15], s[28:29], 20
	s_mul_hi_i32 s1, s0, 0x60000
	s_mul_i32 s0, s0, 0x60000
	v_and_b32_e32 v4, 32, v4
	v_bfe_i32 v14, v1, 0, 16
	s_add_u32 s30, s3, s0
	v_mul_u32_u24_e32 v3, 0x300, v3
	v_add_u32_e32 v1, v4, v14
	s_addc_u32 s31, s36, s1
	s_add_i32 s0, s2, 0
	v_add_lshl_u32 v132, v3, v1, 1
	s_add_i32 m0, s0, 0x10000
	v_lshlrev_b32_e32 v0, 12, v0
	global_load_lds_dwordx4 v132, s[30:31]
	s_add_i32 m0, s0, 0x12000
	s_add_u32 s18, s30, 0x30000
	global_load_lds_dwordx4 v128, s[30:31]
	s_addc_u32 s19, s31, 0
	s_add_i32 m0, s0, 0x14000
	v_lshl_add_u32 v134, v1, 1, v0
	global_load_lds_dwordx4 v132, s[18:19]
	s_add_i32 m0, s0, 0x16000
	s_add_u32 s34, s37, s14
	s_addc_u32 s35, s38, s15
	s_add_i32 s1, s0, 0x2000
	global_load_lds_dwordx4 v128, s[18:19]
	s_mov_b32 m0, s0
	s_add_u32 s14, s34, 0x80000
	global_load_lds_dwordx4 v134, s[34:35]
	s_mov_b32 m0, s1
	s_addc_u32 s15, s35, 0
	s_add_i32 s29, s0, 0x4000
	global_load_lds_dwordx4 v130, s[34:35]
	s_mov_b32 m0, s29
	s_add_i32 s40, s0, 0x6000
	global_load_lds_dwordx4 v134, s[14:15]
	s_mov_b32 m0, s40
	v_mov_b32_e32 v133, 0
	global_load_lds_dwordx4 v130, s[14:15]
	v_mov_b32_e32 v129, v133
	v_mov_b32_e32 v135, v133
	v_mov_b32_e32 v131, v133
	s_cmp_eq_u32 s5, 1
	s_mov_b32 s41, 0
	v_lshl_add_u64 v[6:7], s[30:31], 0, v[132:133]
	v_lshl_add_u64 v[4:5], s[30:31], 0, v[128:129]
	v_lshl_add_u64 v[0:1], s[34:35], 0, v[134:135]
	s_cselect_b64 s[14:15], -1, 0
	s_cmp_lg_u32 s5, 1
	v_lshl_add_u64 v[2:3], s[34:35], 0, v[130:131]
	s_cbranch_scc1 .LBB0_395
	s_nop 0
.LBB0_395:
	s_lshl_b32 s16, s16, 5
	s_and_b32 s20, s16, 0x60
	s_mov_b64 s[16:17], 0x80
	s_add_i32 m0, s0, 0x18000
	v_lshl_add_u64 v[6:7], v[6:7], 0, s[16:17]
	s_lshl_b32 s7, s5, 13
	s_lshl_b32 s21, s20, 7
	global_load_lds_dwordx4 v[6:7], off
	v_lshl_add_u64 v[4:5], v[4:5], 0, s[16:17]
	s_add_i32 m0, s0, 0x1a000
	s_add_i32 s42, s0, 0x8000
	s_add_i32 s43, s0, 0xa000
	global_load_lds_dwordx4 v[4:5], off
	v_lshl_add_u64 v[0:1], v[0:1], 0, s[16:17]
	s_mov_b32 m0, s42
	s_add_u32 s18, s30, 0x30080
	global_load_lds_dwordx4 v[0:1], off
	v_lshl_add_u64 v[0:1], v[2:3], 0, s[16:17]
	s_mov_b32 m0, s43
	s_addc_u32 s19, s31, 0
	global_load_lds_dwordx4 v[0:1], off
	s_add_i32 m0, s0, 0x1c000
	v_lshl_add_u64 v[0:1], s[18:19], 0, v[132:133]
	global_load_lds_dwordx4 v[0:1], off
	v_lshl_add_u64 v[0:1], s[18:19], 0, v[128:129]
	s_add_i32 m0, s0, 0x1e000
	s_cmpk_lt_u32 s4, 0x100
	global_load_lds_dwordx4 v[0:1], off
	s_cselect_b32 s97, 1, 0
	v_readfirstlane_b32 s101, v193
	s_nop 3
	s_lshr_b32 s101, s101, 6
	s_cmp_lt_u32 s101, 4
	s_cbranch_scc1 .Lpro_skip_3
	s_barrier
.Lpro_skip_3:
	s_waitcnt vmcnt(8)
	s_barrier
	s_cmp_lg_u32 s97, 0
	v_lshrrev_b32_e32 v1, 1, v9
	v_and_b32_e32 v1, 24, v1
	v_and_b32_e32 v0, 15, v9
	v_lshlrev_b32_e32 v2, 1, v1
	v_lshl_or_b32 v146, s5, 6, v0
	v_lshl_or_b32 v0, v0, 6, v2
	v_lshlrev_b32_e32 v2, 2, v9
	v_and_b32_e32 v2, 32, v2
	v_bitop3_b32 v3, v0, s7, v2 bitop3:0xde
	v_bitop3_b32 v147, v0, s21, v2 bitop3:0xde
	v_lshlrev_b32_e32 v0, 15, v13
	v_and_b32_e32 v0, 0xffff0000, v0
	v_or_b32_e32 v148, s20, v1
	v_lshl_add_u32 v0, v12, 12, v0
	v_and_b32_e32 v1, 1, v13
	v_lshl_or_b32 v0, v1, 6, v0
	v_lshl_add_u32 v136, v14, 1, v0
	v_lshlrev_b32_e32 v0, 15, v8
	v_and_b32_e32 v0, 0xffff0000, v0
	s_waitcnt vmcnt(6)
	v_lshl_add_u32 v0, v10, 12, v0
	v_and_b32_e32 v1, 1, v8
	s_cselect_b64 s[18:19], -1, 0
	v_lshl_or_b32 v0, v1, 6, v0
	s_add_i32 s45, 0, 0x10000
	s_add_i32 s46, 0, 0x14000
	s_sext_i32_i8 s49, s6
	v_mov_b32_e32 v137, v133
	v_lshl_add_u32 v138, v11, 1, v0
	v_mov_b32_e32 v139, v133
	v_mov_b64_e32 v[140:141], 0x240
	v_mov_b64_e32 v[142:143], 0x23f
	s_mov_b64 s[20:21], 0x100
	v_add_u32_e32 v149, s45, v147
	v_add_u32_e32 v150, s46, v147
	v_add_u32_e32 v151, 0, v3
	s_movk_i32 s47, 0x1200
	s_barrier
	s_branch .LBB0_398

; #define LAS __attribute__((address_space(3)))
; __device__ __forceinline__ int my_tid() { int t = threadIdx.x; asm volatile("" : "+v"(t)); return t; }
; #define PG8_STAGE(bufoff, gbase, voff) do { _Pragma("unroll") for (int _i = 0; _i < 2; ++_i) \
;         __builtin_amdgcn_global_load_lds((const unsigned*)((const char*)(gbase) + (voff)[_i]), (LAS unsigned*)(lds + (bufoff) + ldsw + _i * 8192), 16, 0, 0); } while (0)
; #define PG8_BAR __builtin_amdgcn_s_barrier()
;     __host__ __device__ bool next(int i, Unit& u) const {
;         const long L = (long)i * G + c; if (L >= nwg) return false;
;         int wgid = (int)L; { const int q = nwg / NXCD, r = nwg % NXCD, xcd = wgid % NXCD, off = wgid / NXCD; wgid = (xcd < r ? xcd * (q + 1) : r * (q + 1) + (xcd - r) * q) + off; }
;         const int nig = WGM * nN, gid = wgid / nig, fm = gid * WGM, gsz = (nM - fm) < WGM ? (nM - fm) : WGM;
;         u.pm = fm + ((wgid % nig) % gsz); u.pn = (wgid % nig) / gsz; return true;
;     }
; template <class Epi, bool ALIGN_EPI>
; __device__ __forceinline__ void gemm_phase(LAS unsigned char* lds, const Gemm g, const StaticOrder& S, const Epi& E) {
;     const int tid = my_tid(), wid = __builtin_amdgcn_readfirstlane(tid >> 6), lane = tid & 63, wr = wid >> 2, wc = wid & 3, fr = lane & 15, fq = lane >> 4;
;     const int nt = g.K / BK;
;     unsigned voffA[2], voffB[2];
; #pragma unroll
;     for (int i = 0; i < 2; ++i) { int R, C; stage_rc(tid * 16 + i * 8192, R, C); const int Rb = Epi::PERM ? ((R & ~31) + perm32(R & 31)) : R;
;         voffA[i] = (unsigned)(R * g.lda + C) * 2u; voffB[i] = (unsigned)(Rb * g.ldb + C) * 2u; }
;     const size_t kstep = (size_t)(BK * 2);
;     const size_t hA = (size_t)HALF * g.lda * 2, hB = (size_t)HALF * g.ldb * 2;
;     const size_t tA = 2 * hA, tB = 2 * hB;
;     const unsigned ldsw = (unsigned)wid * 1024u;
;     const int aoff = lds_byte(wr * 64 + fr, fq * 8), boff = lds_byte(wc * 32 + fr, fq * 8);
;     ...
;     const char* cA = (const char*)g.A + (size_t)cur.pm * tA + (size_t)cur.pn * g.acol; const char* cB = (const char*)g.Bt + (size_t)cur.pn * tB;
;     PG8_STAGE(PG8_SB(0, 0), cB, voffB); PG8_STAGE(PG8_SB(0, 1), cB + hB, voffB); PG8_STAGE(PG8_SA(0, 0), cA, voffA); PG8_STAGE(PG8_SA(0, 1), cA + hA, voffA);
;     if (wr == 1) PG8_BAR;
.LBB0_410:
	s_abs_i32 s0, s76
	v_cvt_f32_u32_e32 v0, s0
	s_add_i32 s1, s84, s76
	s_sub_i32 s2, s1, 64
	s_sub_i32 s1, 64, s1
	v_rcp_iflag_f32_e32 v0, v0
	s_sub_i32 s3, 0, s0
	s_ashr_i32 s4, s2, 31
	s_max_i32 s1, s2, s1
	v_mul_f32_e32 v0, 0x4f7ffffe, v0
	v_cvt_u32_f32_e32 v0, v0
	v_mov_b32_e32 v8, v193
	v_readfirstlane_b32 s2, v0
	s_mul_i32 s3, s3, s2
	s_mul_hi_u32 s3, s2, s3
	s_add_i32 s2, s2, s3
	s_mul_hi_u32 s2, s1, s2
	s_mul_i32 s2, s2, s0
	s_sub_i32 s1, s1, s2
	s_sub_i32 s2, s1, s0
	s_cmp_ge_u32 s1, s0
	s_cselect_b32 s1, s2, s1
	s_sub_i32 s2, s1, s0
	s_cmp_ge_u32 s1, s0
	s_cselect_b32 s0, s2, s1
	s_xor_b32 s0, s0, s4
	s_sub_i32 s0, s0, s4
	s_cmp_gt_i32 s0, 7
	v_readfirstlane_b32 s15, v8
	s_cbranch_scc1 .LBB0_426
	v_lshlrev_b32_e32 v0, 4, v8
	v_add_u32_e32 v1, 0x2000, v0
	v_ashrrev_i32_e32 v2, 31, v1
	v_lshrrev_b32_e32 v2, 22, v2
	v_add_u32_e32 v2, v1, v2
	v_ashrrev_i32_e32 v9, 10, v2
	v_mul_i32_i24_e32 v3, 0x400, v9
	v_sub_u32_e32 v1, v1, v3
	v_lshrrev_b32_e32 v3, 4, v1
	v_bitop3_b32 v1, v3, v1, 32 bitop3:0x6c
	v_ashrrev_i32_e32 v3, 31, v1
	v_lshrrev_b32_e32 v3, 26, v3
	v_add_u32_e32 v3, v1, v3
	s_waitcnt vmcnt(0)
	v_ashrrev_i32_e32 v10, 6, v3
	v_and_b32_e32 v3, 0xc0, v3
	v_sub_u32_e32 v1, v1, v3
	v_mov_b32_e32 v3, 1
	v_ashrrev_i16_sdwa v1, v3, sext(v1) dst_sel:DWORD dst_unused:UNUSED_PAD src0_sel:DWORD src1_sel:BYTE_0
	v_bfe_i32 v11, v1, 0, 16
	v_lshlrev_b32_e32 v1, 3, v9
	v_and_b32_e32 v1, -16, v1
	v_add_u32_e32 v1, v10, v1
	v_lshlrev_b32_e32 v2, 5, v9
	v_and_b32_e32 v4, 3, v10
	s_mov_b32 s4, 0xfffe0
	v_lshrrev_b32_e32 v5, 2, v1
	v_lshlrev_b32_e32 v6, 1, v1
	v_and_b32_e32 v2, 32, v2
	v_and_or_b32 v4, v1, s4, v4
	v_and_b32_e32 v5, 4, v5
	v_and_b32_e32 v6, 24, v6
	v_or3_b32 v4, v4, v5, v6
	v_add_lshl_u32 v2, v2, v11, 1
	v_lshl_add_u32 v128, v4, 12, v2
	v_lshl_add_u32 v130, v1, 12, v2
	v_bfe_i32 v2, v8, 27, 1
	v_lshrrev_b32_e32 v2, 22, v2
	v_add_u32_e32 v2, v0, v2
	v_and_b32_e32 v2, 0xfffffc00, v2
	v_sub_u32_e32 v0, v0, v2
	v_lshrrev_b32_e32 v2, 4, v0
	v_bitop3_b32 v2, v2, v0, 32 bitop3:0x6c
	v_ashrrev_i32_e32 v0, 31, v0
	v_lshrrev_b32_e32 v0, 26, v0
	v_add_u32_e32 v0, v2, v0
	v_ashrrev_i32_e32 v1, 31, v8
	v_ashrrev_i32_e32 v13, 6, v0
	s_ashr_i32 s8, s15, 6
	v_lshrrev_b32_e32 v1, 26, v1
	v_mul_i32_i24_e32 v0, 64, v13
	s_ashr_i32 s16, s15, 8
	s_lshl_b32 s1, s8, 10
	v_add_u32_e32 v1, v8, v1
	v_sub_u32_e32 v0, v2, v0
	s_add_u32 s2, s10, 0x2d60000
	v_ashrrev_i32_e32 v12, 6, v1
	v_ashrrev_i16_sdwa v0, v3, sext(v0) dst_sel:DWORD dst_unused:UNUSED_PAD src0_sel:DWORD src1_sel:BYTE_0
	s_addc_u32 s3, s11, 0
	v_bfe_i32 v14, v0, 0, 16
	v_lshlrev_b32_e32 v0, 3, v12
	s_add_u32 s36, s10, 0x3260000
	v_and_b32_e32 v0, -16, v0
	s_addc_u32 s37, s11, 0
	v_add_u32_e32 v0, v13, v0
	v_and_b32_e32 v2, 3, v13
	s_ashr_i32 s38, s0, 31
	v_and_or_b32 v2, v0, s4, v2
	s_lshr_b32 s4, s38, 29
	s_add_i32 s4, s0, s4
	s_ashr_i32 s5, s4, 3
	s_and_b32 s4, s4, -8
	s_sub_i32 s4, s0, s4
	s_lshr_b32 s6, s4, 31
	s_lshl_b32 s4, s4, s6
	s_add_i32 s4, s4, s5
	s_ashr_i32 s5, s4, 31
	s_lshr_b32 s5, s5, 28
	s_add_i32 s5, s4, s5
	s_ashr_i32 s6, s5, 4
	s_lshl_b32 s6, s6, 2
	v_lshlrev_b32_e32 v1, 5, v12
	v_lshrrev_b32_e32 v3, 2, v0
	v_lshlrev_b32_e32 v4, 1, v0
	s_sub_i32 s7, 2, s6
	v_and_b32_e32 v1, 32, v1
	v_and_b32_e32 v3, 4, v3
	v_and_b32_e32 v4, 24, v4
	s_min_u32 s7, s7, 4
	s_and_b32 s5, s5, -16
	v_or3_b32 v2, v2, v3, v4
	v_add_lshl_u32 v1, v1, v14, 1
	s_sub_i32 s9, s4, s5
	v_cvt_f32_ubyte0_e32 v3, s7
	v_lshl_add_u32 v132, v2, 12, v1
	v_cvt_f32_i32_e32 v2, s9
	v_rcp_iflag_f32_e32 v4, v3
	v_lshl_add_u32 v134, v0, 12, v1
	s_ashr_i32 s4, s9, 30
	s_or_b32 s14, s4, 1
	v_mul_f32_e32 v0, v2, v4
	v_trunc_f32_e32 v0, v0
	v_fma_f32 v1, -v0, v3, v2
	v_cvt_i32_f32_e32 v0, v0
	v_cmp_ge_f32_e64 s[4:5], |v1|, v3
	s_and_b64 s[4:5], s[4:5], exec
	s_cselect_b32 s4, s14, 0
	v_readfirstlane_b32 s5, v0
	s_add_i32 s14, s5, s4
	s_mul_i32 s4, s14, s7
	s_sub_i32 s4, s9, s4
	s_sext_i32_i8 s4, s4
	s_add_i32 s26, s6, s4
	s_ashr_i32 s27, s26, 31
	s_bfe_i64 s[6:7], s[14:15], 0x80000
	s_lshl_b64 s[4:5], s[26:27], 20
	s_lshl_b64 s[6:7], s[6:7], 20
	s_add_u32 s30, s2, s6
	s_addc_u32 s31, s3, s7
	s_add_i32 s27, s1, 0
	s_add_i32 m0, s27, 0x10000
	v_mov_b32_e32 v133, 0
	global_load_lds_dwordx4 v132, s[30:31]
	s_add_i32 m0, s27, 0x12000
	s_add_u32 s6, s30, 0x80000
	global_load_lds_dwordx4 v128, s[30:31]
	s_addc_u32 s7, s31, 0
	s_add_i32 m0, s27, 0x14000
	v_mov_b32_e32 v129, v133
	global_load_lds_dwordx4 v132, s[6:7]
	s_add_i32 m0, s27, 0x16000
	s_add_u32 s28, s36, s4
	s_addc_u32 s29, s37, s5
	s_add_i32 s39, s27, 0x2000
	global_load_lds_dwordx4 v128, s[6:7]
	s_mov_b32 m0, s27
	s_add_u32 s4, s28, 0x80000
	global_load_lds_dwordx4 v134, s[28:29]
	s_mov_b32 m0, s39
	s_addc_u32 s5, s29, 0
	s_add_i32 s40, s27, 0x4000
	global_load_lds_dwordx4 v130, s[28:29]
	s_mov_b32 m0, s40
	s_add_i32 s41, s27, 0x6000
	global_load_lds_dwordx4 v134, s[4:5]
	s_mov_b32 m0, s41
	v_mov_b32_e32 v135, v133
	global_load_lds_dwordx4 v130, s[4:5]
	v_mov_b32_e32 v131, v133
	s_cmp_eq_u32 s16, 1
	v_lshl_add_u64 v[6:7], s[30:31], 0, v[132:133]
	v_lshl_add_u64 v[2:3], s[30:31], 0, v[128:129]
	s_mov_b64 s[4:5], 0x80000
	v_lshl_add_u64 v[0:1], s[28:29], 0, v[134:135]
	s_cselect_b64 s[6:7], -1, 0
	s_cmp_lg_u32 s16, 1
	v_lshl_add_u64 v[4:5], s[28:29], 0, v[130:131]
	s_cbranch_scc1 .LBB0_413
	s_nop 0
; #define PG8_STAGE(bufoff, gbase, voff) do { _Pragma("unroll") for (int _i = 0; _i < 2; ++_i) \
;         __builtin_amdgcn_global_load_lds((const unsigned*)((const char*)(gbase) + (voff)[_i]), (LAS unsigned*)(lds + (bufoff) + ldsw + _i * 8192), 16, 0, 0); } while (0)
; #define PG8_WAIT_V(n) asm volatile("s_waitcnt vmcnt(" #n ")" ::: "memory")
; #define PG8_BAR __builtin_amdgcn_s_barrier()
; template <class Epi, bool ALIGN_EPI>
; __device__ __forceinline__ void gemm_phase(LAS unsigned char* lds, const Gemm g, const StaticOrder& S, const Epi& E) {
;     ...
;     PG8_STAGE(PG8_SB(1, 0), cB + kstep, voffB); PG8_STAGE(PG8_SA(1, 0), cA + kstep, voffA); PG8_STAGE(PG8_SB(1, 1), cB + hB + kstep, voffB);
;     PG8_WAIT_V(6); PG8_BAR;
.LBB0_413:
	s_lshl_b32 s8, s8, 5
	s_and_b32 s20, s8, 0x60
	s_lshl_b32 s17, s16, 13
	s_lshl_b32 s21, s20, 7
	s_add_u32 s8, s10, 0x3460000
	s_addc_u32 s9, s11, 0
	s_mov_b64 s[10:11], 0x80
	s_add_i32 m0, s27, 0x18000
	v_lshl_add_u64 v[6:7], v[6:7], 0, s[10:11]
	global_load_lds_dwordx4 v[6:7], off
	v_lshl_add_u64 v[2:3], v[2:3], 0, s[10:11]
	s_add_i32 m0, s27, 0x1a000
	s_add_i32 s42, s27, 0x8000
	s_add_i32 s43, s27, 0xa000
	global_load_lds_dwordx4 v[2:3], off
	v_lshl_add_u64 v[0:1], v[0:1], 0, s[10:11]
	s_mov_b32 m0, s42
	s_add_u32 s18, s30, 0x80080
	global_load_lds_dwordx4 v[0:1], off
	v_lshl_add_u64 v[0:1], v[4:5], 0, s[10:11]
	s_mov_b32 m0, s43
	s_addc_u32 s19, s31, 0
	global_load_lds_dwordx4 v[0:1], off
	s_add_i32 m0, s27, 0x1c000
	v_lshl_add_u64 v[0:1], s[18:19], 0, v[132:133]
	global_load_lds_dwordx4 v[0:1], off
	v_lshl_add_u64 v[0:1], s[18:19], 0, v[128:129]
	s_add_i32 m0, s27, 0x1e000
	s_cmpk_lt_u32 s15, 0x100
	global_load_lds_dwordx4 v[0:1], off
	s_cselect_b32 s97, 1, 0
	v_readfirstlane_b32 s101, v193
	s_nop 3
	s_lshr_b32 s101, s101, 6
	s_cmp_lt_u32 s101, 4
	s_cbranch_scc1 .Lpro_skip_4
	s_barrier
.Lpro_skip_4:
	s_waitcnt vmcnt(8)
	s_barrier
	s_cmp_lg_u32 s97, 0
	v_bfe_u32 v0, v8, 4, 2
	v_and_b32_e32 v1, 15, v8
	v_lshlrev_b32_e32 v2, 4, v0
	v_lshl_or_b32 v142, s16, 6, v1
	v_lshl_or_b32 v1, v1, 6, v2
	v_lshlrev_b32_e32 v2, 2, v8
	v_lshl_or_b32 v144, v0, 3, s20
	v_lshlrev_b32_e32 v0, 15, v12
	v_and_b32_e32 v2, 32, v2
	v_and_b32_e32 v0, 0xffff0000, v0
	v_bitop3_b32 v3, v1, s17, v2 bitop3:0xde
	v_bitop3_b32 v143, v1, s21, v2 bitop3:0xde
	v_lshl_add_u32 v0, v13, 12, v0
	v_and_b32_e32 v1, 1, v12
	v_lshl_or_b32 v0, v1, 6, v0
	v_lshl_add_u32 v136, v14, 1, v0
	v_lshlrev_b32_e32 v0, 15, v9
	v_and_b32_e32 v0, 0xffff0000, v0
	s_waitcnt vmcnt(6)
	v_lshl_add_u32 v0, v10, 12, v0
	v_and_b32_e32 v1, 1, v9
	s_sext_i32_i8 s48, s14
	s_cselect_b64 s[14:15], -1, 0
	v_lshl_or_b32 v0, v1, 6, v0
	s_add_i32 s45, 0, 0x10000
	s_add_i32 s46, 0, 0x14000
	s_mov_b32 s44, 0
	v_mov_b32_e32 v137, v133
	v_lshl_add_u32 v138, v11, 1, v0
	v_mov_b32_e32 v139, v133
	v_add_u32_e32 v145, s45, v143
	v_add_u32_e32 v146, s46, v143
	v_add_u32_e32 v147, 0, v3
	s_mov_b32 s47, 0x80000
	s_barrier
	s_branch .LBB0_416

; __device__ __forceinline__ int my_tid() { int t = threadIdx.x; asm volatile("" : "+v"(t)); return t; }
; #define PG8_STAGE(bufoff, gbase, voff) do { _Pragma("unroll") for (int _i = 0; _i < 2; ++_i) \
;         __builtin_amdgcn_global_load_lds((const unsigned*)((const char*)(gbase) + (voff)[_i]), (LAS unsigned*)(lds + (bufoff) + ldsw + _i * 8192), 16, 0, 0); } while (0)
; #define PG8_WAIT_V(n) asm volatile("s_waitcnt vmcnt(" #n ")" ::: "memory")
; #define PG8_BAR __builtin_amdgcn_s_barrier()
; template <class Epi, bool ALIGN_EPI>
; __device__ __forceinline__ void gemm_phase(LAS unsigned char* lds, const Gemm g, const StaticOrder& S, const Epi& E) {
;     const int tid = my_tid(), wid = __builtin_amdgcn_readfirstlane(tid >> 6), lane = tid & 63, wr = wid >> 2, wc = wid & 3, fr = lane & 15, fq = lane >> 4;
;     const int nt = g.K / BK;
;     unsigned voffA[2], voffB[2];
; #pragma unroll
;     for (int i = 0; i < 2; ++i) { int R, C; stage_rc(tid * 16 + i * 8192, R, C); const int Rb = Epi::PERM ? ((R & ~31) + perm32(R & 31)) : R;
;         voffA[i] = (unsigned)(R * g.lda + C) * 2u; voffB[i] = (unsigned)(Rb * g.ldb + C) * 2u; }
;     const size_t kstep = (size_t)(BK * 2);
;     const size_t hA = (size_t)HALF * g.lda * 2, hB = (size_t)HALF * g.ldb * 2;
;     const size_t tA = 2 * hA, tB = 2 * hB;
;     const unsigned ldsw = (unsigned)wid * 1024u;
;     const int aoff = lds_byte(wr * 64 + fr, fq * 8), boff = lds_byte(wc * 32 + fr, fq * 8);
;     ...
;     const char* cA = (const char*)g.A + (size_t)cur.pm * tA + (size_t)cur.pn * g.acol; const char* cB = (const char*)g.Bt + (size_t)cur.pn * tB;
;     PG8_STAGE(PG8_SB(0, 0), cB, voffB); PG8_STAGE(PG8_SB(0, 1), cB + hB, voffB); PG8_STAGE(PG8_SA(0, 0), cA, voffA); PG8_STAGE(PG8_SA(0, 1), cA + hA, voffA);
;     if (wr == 1) PG8_BAR;
;     PG8_WAIT_V(2); PG8_BAR;
;     PG8_STAGE(PG8_SB(1, 0), cB + kstep, voffB); PG8_STAGE(PG8_SA(1, 0), cA + kstep, voffA); PG8_STAGE(PG8_SB(1, 1), cB + hB + kstep, voffB);
;     PG8_WAIT_V(6); PG8_BAR;
.LBB0_762:
	s_andn2_b64 vcc, exec, s[4:5]
	s_cbranch_vccnz .LBB0_858
	v_ashrrev_i32_e32 v1, 31, v8
	v_lshrrev_b32_e32 v1, 26, v1
	v_add_u32_e32 v1, v8, v1
	s_waitcnt vmcnt(0)
	v_ashrrev_i32_e32 v9, 6, v1
	v_bfe_i32 v1, v8, 27, 1
	v_lshlrev_b32_e32 v0, 4, v8
	v_lshrrev_b32_e32 v1, 22, v1
	v_add_u32_e32 v1, v0, v1
	v_and_b32_e32 v1, 0xfffffc00, v1
	v_sub_u32_e32 v1, v0, v1
	v_lshrrev_b32_e32 v2, 4, v1
	v_bitop3_b32 v2, v2, v1, 32 bitop3:0x6c
	v_ashrrev_i32_e32 v1, 31, v1
	v_lshrrev_b32_e32 v1, 26, v1
	v_add_u32_e32 v1, v2, v1
	v_ashrrev_i32_e32 v10, 6, v1
	v_lshlrev_b32_e32 v3, 3, v9
	v_mul_i32_i24_e32 v4, 64, v10
	v_and_b32_e32 v3, -16, v3
	v_sub_u32_e32 v2, v2, v4
	v_mov_b32_e32 v4, 1
	v_add_u32_e32 v1, v10, v3
	v_lshlrev_b32_e32 v3, 5, v9
	v_ashrrev_i16_sdwa v2, v4, sext(v2) dst_sel:DWORD dst_unused:UNUSED_PAD src0_sel:DWORD src1_sel:BYTE_0
	v_and_b32_e32 v3, 32, v3
	v_bfe_i32 v11, v2, 0, 16
	v_and_b32_e32 v6, 3, v10
	s_mov_b32 s2, 0xfffe0
	v_add_lshl_u32 v3, v3, v11, 1
	v_add_u32_e32 v0, 0x2000, v0
	v_lshlrev_b32_e32 v2, 1, v1
	v_lshrrev_b32_e32 v5, 2, v1
	v_and_or_b32 v6, v1, s2, v6
	v_lshl_add_u32 v160, v1, 12, v3
	v_ashrrev_i32_e32 v1, 31, v0
	v_lshrrev_b32_e32 v1, 22, v1
	v_add_u32_e32 v1, v0, v1
	v_ashrrev_i32_e32 v12, 10, v1
	v_mul_i32_i24_e32 v1, 0x400, v12
	v_sub_u32_e32 v0, v0, v1
	v_and_b32_e32 v2, 24, v2
	v_and_b32_e32 v5, 4, v5
	v_lshrrev_b32_e32 v1, 4, v0
	s_load_dwordx2 s[4:5], s[6:7], 0xe0
	s_load_dwordx2 s[12:13], s[6:7], 0x0
	v_or3_b32 v2, v6, v5, v2
	v_bitop3_b32 v0, v1, v0, 32 bitop3:0x6c
	v_lshl_add_u32 v162, v2, 12, v3
	v_ashrrev_i32_e32 v2, 31, v0
	v_lshrrev_b32_e32 v2, 26, v2
	v_add_u32_e32 v2, v0, v2
	s_waitcnt lgkmcnt(0)
	s_add_u32 s33, s4, 0xf60000
	v_lshlrev_b32_e32 v1, 3, v12
	v_ashrrev_i32_e32 v13, 6, v2
	v_and_b32_e32 v2, 0xc0, v2
	s_addc_u32 s46, s5, 0
	v_and_b32_e32 v1, -16, v1
	v_sub_u32_e32 v0, v0, v2
	s_add_u32 s47, s4, 0x8000000
	v_add_u32_e32 v1, v13, v1
	v_ashrrev_i16_sdwa v0, v4, sext(v0) dst_sel:DWORD dst_unused:UNUSED_PAD src0_sel:DWORD src1_sel:BYTE_0
	v_and_b32_e32 v4, 3, v13
	s_addc_u32 s48, s5, 0
	v_and_or_b32 v4, v1, s2, v4
	s_ashr_i32 s2, s0, 6
	s_ashr_i32 s9, s8, 31
	s_ashr_i32 s37, s36, 31
	s_ashr_i32 s1, s0, 8
	s_lshl_b32 s49, s2, 10
	s_lshl_b64 s[6:7], s[8:9], 20
	s_lshl_b64 s[14:15], s[36:37], 20
	s_add_u32 s42, s33, s14
	v_lshlrev_b32_e32 v3, 5, v12
	v_bfe_i32 v14, v0, 0, 16
	v_lshlrev_b32_e32 v0, 1, v1
	v_lshrrev_b32_e32 v2, 2, v1
	s_addc_u32 s43, s46, s15
	s_add_i32 s50, s49, 0
	v_and_b32_e32 v3, 32, v3
	v_and_b32_e32 v0, 24, v0
	v_and_b32_e32 v2, 4, v2
	s_add_i32 m0, s50, 0x10000
	v_or3_b32 v0, v4, v2, v0
	v_add_lshl_u32 v2, v3, v14, 1
	global_load_lds_dwordx4 v162, s[42:43]
	s_add_i32 m0, s50, 0x12000
	v_lshl_add_u32 v166, v0, 12, v2
	s_add_u32 s14, s42, 0x80000
	global_load_lds_dwordx4 v166, s[42:43]
	s_addc_u32 s15, s43, 0
	s_add_i32 m0, s50, 0x14000
	v_lshl_add_u32 v164, v1, 12, v2
	global_load_lds_dwordx4 v162, s[14:15]
	s_add_i32 m0, s50, 0x16000
	s_add_u32 s40, s47, s6
	s_addc_u32 s41, s48, s7
	s_add_i32 s51, s50, 0x2000
	global_load_lds_dwordx4 v166, s[14:15]
	s_mov_b32 m0, s50
	s_add_u32 s6, s40, 0x80000
	global_load_lds_dwordx4 v160, s[40:41]
	s_mov_b32 m0, s51
	s_addc_u32 s7, s41, 0
	s_add_i32 s52, s50, 0x4000
	global_load_lds_dwordx4 v164, s[40:41]
	s_mov_b32 m0, s52
	s_add_i32 s53, s50, 0x6000
	global_load_lds_dwordx4 v160, s[6:7]
	s_mov_b32 m0, s53
	v_mov_b32_e32 v163, 0
	global_load_lds_dwordx4 v164, s[6:7]
	v_mov_b32_e32 v167, v163
	v_mov_b32_e32 v161, v163
	v_mov_b32_e32 v165, v163
	s_cmp_eq_u32 s1, 1
	s_mov_b32 s54, 0
	v_lshl_add_u64 v[6:7], s[42:43], 0, v[162:163]
	v_lshl_add_u64 v[4:5], s[42:43], 0, v[166:167]
	v_lshl_add_u64 v[0:1], s[40:41], 0, v[160:161]
	s_cselect_b64 s[14:15], -1, 0
	s_cmp_lg_u32 s1, 1
	v_lshl_add_u64 v[2:3], s[40:41], 0, v[164:165]
	s_cbranch_scc1 .LBB0_765
	s_nop 0
.LBB0_765:
	s_ashr_i32 s55, s76, 31
	s_ashr_i32 s56, s84, 31
	s_add_u32 s16, s4, 0xc000000
	s_addc_u32 s17, s5, 0
	s_add_u32 s18, s4, 0x50000
	s_addc_u32 s19, s5, 0
	s_lshl_b32 s2, s2, 5
	s_mov_b64 s[20:21], 0x80
	s_and_b32 s6, s2, 0x60
	s_add_i32 m0, s50, 0x18000
	v_lshl_add_u64 v[6:7], v[6:7], 0, s[20:21]
	s_lshl_b32 s4, s1, 13
	s_lshl_b32 s5, s6, 7
	global_load_lds_dwordx4 v[6:7], off
	v_lshl_add_u64 v[4:5], v[4:5], 0, s[20:21]
	s_add_i32 m0, s50, 0x1a000
	s_add_i32 s57, s50, 0x8000
	s_add_i32 s58, s50, 0xa000
	global_load_lds_dwordx4 v[4:5], off
	v_lshl_add_u64 v[0:1], v[0:1], 0, s[20:21]
	s_mov_b32 m0, s57
	s_add_u32 s2, s42, 0x80080
	global_load_lds_dwordx4 v[0:1], off
	v_lshl_add_u64 v[0:1], v[2:3], 0, s[20:21]
	s_mov_b32 m0, s58
	s_addc_u32 s3, s43, 0
	global_load_lds_dwordx4 v[0:1], off
	s_add_i32 m0, s50, 0x1c000
	v_lshl_add_u64 v[0:1], s[2:3], 0, v[162:163]
	global_load_lds_dwordx4 v[0:1], off
	v_lshl_add_u64 v[0:1], s[2:3], 0, v[166:167]
	s_add_i32 m0, s50, 0x1e000
	s_cmpk_lt_u32 s0, 0x100
	global_load_lds_dwordx4 v[0:1], off
	s_cselect_b32 s97, 1, 0
	v_readfirstlane_b32 s101, v193
	s_nop 3
	s_lshr_b32 s101, s101, 6
	s_cmp_lt_u32 s101, 4
	s_cbranch_scc1 .Lpro_skip_5
	s_barrier
.Lpro_skip_5:
	s_waitcnt vmcnt(8)
	s_barrier
	s_cmp_lg_u32 s97, 0
	v_bfe_u32 v0, v8, 4, 2
	v_and_b32_e32 v1, 15, v8
	v_lshlrev_b32_e32 v2, 4, v0
	v_lshl_or_b32 v192, s1, 6, v1
	v_lshl_or_b32 v1, v1, 6, v2
	v_lshlrev_b32_e32 v2, 2, v8
	v_and_b32_e32 v2, 32, v2
	v_bitop3_b32 v3, v1, s4, v2 bitop3:0xde
	v_bitop3_b32 v194, v1, s5, v2 bitop3:0xde
	v_cmp_eq_u32_e64 s[4:5], 0, v0
	v_lshl_or_b32 v195, v0, 3, s6
	v_lshlrev_b32_e32 v0, 15, v9
	v_and_b32_e32 v0, 0xffff0000, v0
	v_lshl_add_u32 v0, v10, 12, v0
	v_and_b32_e32 v1, 1, v9
	v_lshl_or_b32 v0, v1, 6, v0
	v_lshl_add_u32 v168, v11, 1, v0
	v_lshlrev_b32_e32 v0, 15, v12
	v_and_b32_e32 v0, 0xffff0000, v0
	v_lshl_add_u32 v0, v13, 12, v0
	v_and_b32_e32 v1, 1, v12
	s_waitcnt vmcnt(6)
	s_cselect_b64 s[22:23], -1, 0
	s_cmp_lg_u64 s[12:13], 0
	v_lshl_or_b32 v0, v1, 6, v0
	s_cselect_b64 s[24:25], -1, 0
	v_lshl_add_u32 v170, v14, 1, v0
	s_add_i32 s60, 0, 0x10000
	s_add_i32 s61, 0, 0x14000
	v_mbcnt_lo_u32_b32 v0, -1, 0
	s_mov_b32 s59, s76
	v_mov_b32_e32 v169, v163
	v_mov_b32_e32 v171, v163
	v_mov_b64_e32 v[172:173], 0x200
	v_mov_b64_e32 v[174:175], 0x1ff
	v_add_u32_e32 v196, s60, v194
	v_add_u32_e32 v197, s61, v194
	v_add_u32_e32 v198, 0, v3
	v_mbcnt_hi_u32_b32 v199, -1, v0
	s_mov_b32 s62, 0
	s_barrier
	s_branch .LBB0_768

; __device__ __forceinline__ int my_tid() { int t = threadIdx.x; asm volatile("" : "+v"(t)); return t; }
; #define PG8_STAGE(bufoff, gbase, voff) do { _Pragma("unroll") for (int _i = 0; _i < 2; ++_i) \
;         __builtin_amdgcn_global_load_lds((const unsigned*)((const char*)(gbase) + (voff)[_i]), (LAS unsigned*)(lds + (bufoff) + ldsw + _i * 8192), 16, 0, 0); } while (0)
; #define PG8_BAR __builtin_amdgcn_s_barrier()
; template <class Epi, bool ALIGN_EPI>
; __device__ __forceinline__ void gemm_phase(LAS unsigned char* lds, const Gemm g, const StaticOrder& S, const Epi& E) {
;     const int tid = my_tid(), wid = __builtin_amdgcn_readfirstlane(tid >> 6), lane = tid & 63, wr = wid >> 2, wc = wid & 3, fr = lane & 15, fq = lane >> 4;
;     const int nt = g.K / BK;
;     unsigned voffA[2], voffB[2];
; #pragma unroll
;     for (int i = 0; i < 2; ++i) { int R, C; stage_rc(tid * 16 + i * 8192, R, C); const int Rb = Epi::PERM ? ((R & ~31) + perm32(R & 31)) : R;
;         voffA[i] = (unsigned)(R * g.lda + C) * 2u; voffB[i] = (unsigned)(Rb * g.ldb + C) * 2u; }
;     const size_t kstep = (size_t)(BK * 2);
;     const size_t hA = (size_t)HALF * g.lda * 2, hB = (size_t)HALF * g.ldb * 2;
;     const size_t tA = 2 * hA, tB = 2 * hB;
;     const unsigned ldsw = (unsigned)wid * 1024u;
;     const int aoff = lds_byte(wr * 64 + fr, fq * 8), boff = lds_byte(wc * 32 + fr, fq * 8);
;     ...
;     const char* cA = (const char*)g.A + (size_t)cur.pm * tA + (size_t)cur.pn * g.acol; const char* cB = (const char*)g.Bt + (size_t)cur.pn * tB;
;     PG8_STAGE(PG8_SB(0, 0), cB, voffB); PG8_STAGE(PG8_SB(0, 1), cB + hB, voffB); PG8_STAGE(PG8_SA(0, 0), cA, voffA); PG8_STAGE(PG8_SA(0, 1), cA + hA, voffA);
;     if (wr == 1) PG8_BAR;
.LBB0_912:
	s_cmp_lt_i32 s80, 9
	s_cselect_b64 s[10:11], -1, 0
	s_cmp_gt_i32 s81, 8
	s_cselect_b64 s[0:1], -1, 0
	s_and_b64 s[0:1], s[10:11], s[0:1]
	s_andn2_b64 vcc, exec, s[0:1]
	s_cbranch_vccnz .LBB0_935
	s_mov_b64 s[4:5], s[78:79]
	v_mov_b32_e32 v0, v193
	v_mov_b32_e32 v8, v193
	s_cmpk_gt_i32 s84, 0x7ff
	s_nop 0
	v_readfirstlane_b32 s21, v8
	s_cbranch_scc1 .LBB0_935
	v_lshlrev_b32_e32 v0, 4, v8
	s_waitcnt lgkmcnt(0)
	v_add_u32_e32 v1, 0x2000, v0
	v_ashrrev_i32_e32 v2, 31, v1
	v_lshrrev_b32_e32 v2, 22, v2
	v_add_u32_e32 v2, v1, v2
	s_waitcnt vmcnt(0)
	v_ashrrev_i32_e32 v9, 10, v2
	v_mul_i32_i24_e32 v2, 0x400, v9
	v_sub_u32_e32 v1, v1, v2
	v_lshrrev_b32_e32 v2, 4, v1
	v_bitop3_b32 v1, v2, v1, 32 bitop3:0x6c
	v_ashrrev_i32_e32 v2, 31, v1
	v_lshrrev_b32_e32 v2, 26, v2
	v_add_u32_e32 v2, v1, v2
	v_lshlrev_b32_e32 v3, 3, v9
	v_ashrrev_i32_e32 v11, 6, v2
	v_and_b32_e32 v3, -16, v3
	v_add_u32_e32 v3, v11, v3
	v_and_b32_e32 v4, 3, v11
	s_mov_b32 s6, 0xfffe0
	v_lshrrev_b32_e32 v5, 2, v3
	v_lshlrev_b32_e32 v6, 1, v3
	v_and_b32_e32 v2, 0xc0, v2
	v_and_or_b32 v4, v3, s6, v4
	v_and_b32_e32 v5, 4, v5
	v_and_b32_e32 v6, 24, v6
	v_sub_u32_e32 v1, v1, v2
	v_mov_b32_e32 v2, 1
	v_or3_b32 v4, v4, v5, v6
	v_lshlrev_b32_e32 v5, 5, v9
	v_ashrrev_i16_sdwa v1, v2, sext(v1) dst_sel:DWORD dst_unused:UNUSED_PAD src0_sel:DWORD src1_sel:BYTE_0
	v_and_b32_e32 v5, 32, v5
	v_bfe_i32 v12, v1, 0, 16
	v_add_lshl_u32 v1, v5, v12, 1
	v_lshl_add_u32 v128, v4, 12, v1
	v_lshl_add_u32 v130, v3, 12, v1
	v_bfe_i32 v1, v8, 27, 1
	v_lshrrev_b32_e32 v1, 22, v1
	v_add_u32_e32 v1, v0, v1
	v_and_b32_e32 v1, 0xfffffc00, v1
	v_sub_u32_e32 v0, v0, v1
	s_load_dwordx2 s[4:5], s[4:5], 0xe0
	v_lshrrev_b32_e32 v1, 4, v0
	v_bitop3_b32 v1, v1, v0, 32 bitop3:0x6c
	v_ashrrev_i32_e32 v0, 31, v0
	v_lshrrev_b32_e32 v0, 26, v0
	v_add_u32_e32 v0, v1, v0
	v_ashrrev_i32_e32 v13, 6, v0
	v_ashrrev_i32_e32 v0, 31, v8
	s_waitcnt lgkmcnt(0)
	s_add_u32 s12, s4, 0x50000
	v_lshrrev_b32_e32 v0, 26, v0
	s_addc_u32 s13, s5, 0
	v_add_u32_e32 v0, v8, v0
	s_add_u32 s0, s4, 0xc000000
	v_ashrrev_i32_e32 v14, 6, v0
	s_addc_u32 s1, s5, 0
	v_lshlrev_b32_e32 v0, 3, v14
	s_add_u32 s2, s4, 0x4000000
	v_and_b32_e32 v0, -16, v0
	s_addc_u32 s3, s5, 0
	v_add_u32_e32 v0, v13, v0
	v_and_b32_e32 v3, 3, v13
	s_ashr_i32 s38, s84, 31
	v_and_or_b32 v3, v0, s6, v3
	s_lshr_b32 s6, s38, 29
	s_add_i32 s6, s84, s6
	s_and_b32 s7, s6, -8
	s_ashr_i32 s19, s21, 8
	s_ashr_i32 s18, s21, 6
	s_sub_i32 s7, s84, s7
	s_lshl_b32 s33, s18, 10
	s_lshl_b32 s22, s19, 6
	s_lshl_b32 s9, s7, 8
	s_ashr_i32 s6, s6, 3
	s_mul_i32 s8, s7, 0x101
	s_cmp_lt_i32 s7, 0
	s_cselect_b32 s7, s8, s9
	s_add_i32 s6, s7, s6
	s_ashr_i32 s7, s6, 31
	s_lshr_b32 s7, s7, 25
	s_add_i32 s7, s6, s7
	s_ashr_i32 s8, s7, 7
	s_and_b32 s7, s7, 0xffffff80
	s_sub_i32 s6, s6, s7
	s_bfe_i32 s7, s6, 0x80000
	s_bfe_u32 s7, s7, 0x2000d
	v_lshrrev_b32_e32 v4, 2, v0
	v_lshlrev_b32_e32 v5, 1, v0
	s_add_i32 s7, s6, s7
	v_and_b32_e32 v4, 4, v4
	v_and_b32_e32 v5, 24, v5
	s_bfe_i32 s9, s7, 0x80000
	s_and_b32 s7, s7, 0xfc
	v_or3_b32 v3, v3, v4, v5
	v_mul_i32_i24_e32 v5, 64, v13
	s_sub_i32 s6, s6, s7
	v_sub_u32_e32 v1, v1, v5
	s_lshl_b32 s8, s8, 2
	s_sext_i32_i8 s6, s6
	v_lshlrev_b32_e32 v4, 5, v14
	v_ashrrev_i16_sdwa v1, v2, sext(v1) dst_sel:DWORD dst_unused:UNUSED_PAD src0_sel:DWORD src1_sel:BYTE_0
	s_sext_i32_i16 s9, s9
	s_add_i32 s52, s8, s6
	v_and_b32_e32 v4, 32, v4
	v_bfe_i32 v15, v1, 0, 16
	s_lshr_b32 s20, s9, 2
	s_lshl_b32 s6, s52, 8
	v_and_b32_e32 v10, 15, v8
	v_add_lshl_u32 v1, v4, v15, 1
	s_add_i32 s6, s6, s22
	s_ashr_i32 s53, s52, 31
	s_bfe_i64 s[8:9], s[20:21], 0x100000
	v_lshl_add_u32 v134, v0, 12, v1
	v_or_b32_e32 v0, s6, v10
	s_lshl_b64 s[6:7], s[52:53], 20
	s_lshl_b64 s[8:9], s[8:9], 20
	s_add_u32 s8, s2, s8
	v_lshl_add_u32 v132, v3, 12, v1
	v_ashrrev_i32_e32 v1, 31, v0
	s_addc_u32 s9, s3, s9
	s_add_i32 s39, s33, 0
	v_lshl_add_u64 v[0:1], v[0:1], 2, s[12:13]
	s_add_i32 m0, s39, 0x10000
	global_load_dword v166, v[0:1], off
	global_load_dword v154, v[0:1], off offset:64
	global_load_dword v152, v[0:1], off offset:128
	global_load_dword v150, v[0:1], off offset:192
	global_load_dword v148, v[0:1], off offset:512
	global_load_dword v146, v[0:1], off offset:576
	global_load_dword v145, v[0:1], off offset:640
	global_load_dword v144, v[0:1], off offset:704
	v_mov_b32_e32 v133, 0
	global_load_lds_dwordx4 v132, s[8:9]
	s_add_i32 m0, s39, 0x12000
	s_add_u32 s14, s8, 0x80000
	global_load_lds_dwordx4 v128, s[8:9]
	s_addc_u32 s15, s9, 0
	s_add_i32 m0, s39, 0x14000
	v_mov_b32_e32 v129, v133
	global_load_lds_dwordx4 v132, s[14:15]
	s_add_i32 m0, s39, 0x16000
	s_add_u32 s6, s0, s6
	s_addc_u32 s7, s1, s7
	s_add_i32 s53, s39, 0x2000
	global_load_lds_dwordx4 v128, s[14:15]
	s_mov_b32 m0, s39
	s_add_u32 s14, s6, 0x80000
	global_load_lds_dwordx4 v134, s[6:7]
	s_mov_b32 m0, s53
	s_addc_u32 s15, s7, 0
	s_add_i32 s56, s39, 0x4000
	global_load_lds_dwordx4 v130, s[6:7]
	s_mov_b32 m0, s56
	s_add_i32 s57, s39, 0x6000
	global_load_lds_dwordx4 v134, s[14:15]
	s_mov_b32 m0, s57
	v_mov_b32_e32 v135, v133
	global_load_lds_dwordx4 v130, s[14:15]
	v_mov_b32_e32 v131, v133
	s_cmp_eq_u32 s19, 1
	s_mov_b32 s58, 0
	v_lshl_add_u64 v[6:7], s[8:9], 0, v[132:133]
	v_lshl_add_u64 v[4:5], s[8:9], 0, v[128:129]
	v_lshl_add_u64 v[0:1], s[6:7], 0, v[134:135]
	s_cselect_b64 s[14:15], -1, 0
	s_cmp_lg_u32 s19, 1
	v_lshl_add_u64 v[2:3], s[6:7], 0, v[130:131]
	s_cbranch_scc1 .LBB0_916
	s_nop 0
; #define PG8_STAGE(bufoff, gbase, voff) do { _Pragma("unroll") for (int _i = 0; _i < 2; ++_i) \
;         __builtin_amdgcn_global_load_lds((const unsigned*)((const char*)(gbase) + (voff)[_i]), (LAS unsigned*)(lds + (bufoff) + ldsw + _i * 8192), 16, 0, 0); } while (0)
; #define PG8_WAIT_V(n) asm volatile("s_waitcnt vmcnt(" #n ")" ::: "memory")
; #define PG8_BAR __builtin_amdgcn_s_barrier()
; template <class Epi, bool ALIGN_EPI>
; __device__ __forceinline__ void gemm_phase(LAS unsigned char* lds, const Gemm g, const StaticOrder& S, const Epi& E) {
;     ...
;     PG8_STAGE(PG8_SB(1, 0), cB + kstep, voffB); PG8_STAGE(PG8_SA(1, 0), cA + kstep, voffA); PG8_STAGE(PG8_SB(1, 1), cB + hB + kstep, voffB);
;     PG8_WAIT_V(6); PG8_BAR;
.LBB0_916:
	s_ashr_i32 s59, s76, 31
	s_add_u32 s16, s4, 0x10000000
	s_addc_u32 s17, s5, 0
	s_lshl_b32 s23, s19, 13
	s_lshl_b32 s4, s18, 5
	s_mov_b64 s[18:19], 0x80
	s_and_b32 s24, s4, 0x60
	s_add_i32 m0, s39, 0x18000
	v_lshl_add_u64 v[6:7], v[6:7], 0, s[18:19]
	s_lshl_b32 s25, s24, 7
	global_load_lds_dwordx4 v[6:7], off
	v_lshl_add_u64 v[4:5], v[4:5], 0, s[18:19]
	s_add_i32 m0, s39, 0x1a000
	s_add_i32 s60, s39, 0x8000
	s_add_i32 s61, s39, 0xa000
	global_load_lds_dwordx4 v[4:5], off
	v_lshl_add_u64 v[0:1], v[0:1], 0, s[18:19]
	s_mov_b32 m0, s60
	s_add_u32 s4, s8, 0x80080
	global_load_lds_dwordx4 v[0:1], off
	v_lshl_add_u64 v[0:1], v[2:3], 0, s[18:19]
	s_mov_b32 m0, s61
	s_addc_u32 s5, s9, 0
	global_load_lds_dwordx4 v[0:1], off
	s_add_i32 m0, s39, 0x1c000
	v_lshl_add_u64 v[0:1], s[4:5], 0, v[132:133]
	global_load_lds_dwordx4 v[0:1], off
	v_lshl_add_u64 v[0:1], s[4:5], 0, v[128:129]
	s_add_i32 m0, s39, 0x1e000
	v_or_b32_e32 v147, s22, v10
	global_load_lds_dwordx4 v[0:1], off
	s_cselect_b32 s97, 1, 0
	v_readfirstlane_b32 s101, v193
	s_nop 3
	s_lshr_b32 s101, s101, 6
	s_cmp_lt_u32 s101, 4
	s_cbranch_scc1 .Lpro_skip_6
	s_barrier
.Lpro_skip_6:
	s_waitcnt vmcnt(8)
	s_barrier
	s_cmp_lg_u32 s97, 0
	v_lshrrev_b32_e32 v0, 1, v8
	v_and_b32_e32 v0, 24, v0
	v_lshlrev_b32_e32 v1, 6, v147
	v_lshlrev_b32_e32 v2, 1, v0
	s_movk_i32 s4, 0x3c0
	v_lshlrev_b32_e32 v3, 2, v147
	v_and_or_b32 v1, v1, s4, v2
	v_and_b32_e32 v3, 32, v3
	v_bitop3_b32 v1, v1, s23, v3 bitop3:0xde
	v_lshlrev_b32_e32 v3, 2, v10
	v_or_b32_e32 v151, s24, v0
	v_lshlrev_b32_e32 v0, 15, v14
	v_lshl_or_b32 v2, v10, 6, v2
	v_and_b32_e32 v3, 32, v3
	v_and_b32_e32 v0, 0xffff0000, v0
	v_bitop3_b32 v149, v2, s25, v3 bitop3:0xde
	v_lshl_add_u32 v0, v13, 12, v0
	v_and_b32_e32 v2, 1, v14
	v_lshl_or_b32 v0, v2, 6, v0
	v_lshl_add_u32 v136, v15, 1, v0
	v_lshlrev_b32_e32 v0, 15, v9
	v_and_b32_e32 v0, 0xffff0000, v0
	s_waitcnt vmcnt(6)
	s_cmpk_lt_u32 s21, 0x100
	v_lshl_add_u32 v0, v11, 12, v0
	v_and_b32_e32 v2, 1, v9
	s_sext_i32_i8 s66, s20
	s_cselect_b64 s[20:21], -1, 0
	v_lshl_or_b32 v0, v2, 6, v0
	s_add_i32 s63, 0, 0x10000
	s_add_i32 s64, 0, 0x14000
	s_mov_b32 s62, s76
	v_mov_b32_e32 v137, v133
	v_lshl_add_u32 v138, v12, 1, v0
	v_mov_b32_e32 v139, v133
	v_mov_b64_e32 v[140:141], 0x800
	v_mov_b64_e32 v[142:143], 0x7ff
	s_mov_b64 s[22:23], 0x100
	v_add_u32_e32 v153, s63, v149
	v_add_u32_e32 v155, s64, v149
	v_add_u32_e32 v156, 0, v1
	v_mov_b32_e32 v157, 0x358637bd
	s_mov_b32 s65, 0x800000
	s_mov_b64 s[24:25], 0x200000
	s_mov_b64 s[26:27], 0x200100
	s_mov_b64 s[28:29], 0x240000
	s_mov_b64 s[30:31], 0x240100
	s_mov_b64 s[34:35], 0x280000
	s_mov_b64 s[36:37], 0x280100
	s_mov_b64 s[40:41], 0x2c0000
	s_mov_b64 s[42:43], 0x2c0100
	s_barrier
	s_branch .LBB0_919

; __device__ __forceinline__ int my_tid() { int t = threadIdx.x; asm volatile("" : "+v"(t)); return t; }
; #define PG8_STAGE(bufoff, gbase, voff) do { _Pragma("unroll") for (int _i = 0; _i < 2; ++_i) \
;         __builtin_amdgcn_global_load_lds((const unsigned*)((const char*)(gbase) + (voff)[_i]), (LAS unsigned*)(lds + (bufoff) + ldsw + _i * 8192), 16, 0, 0); } while (0)
; #define PG8_WAIT_V(n) asm volatile("s_waitcnt vmcnt(" #n ")" ::: "memory")
; #define PG8_BAR __builtin_amdgcn_s_barrier()
; template <class Epi, bool ALIGN_EPI>
; __device__ __forceinline__ void gemm_phase(LAS unsigned char* lds, const Gemm g, const StaticOrder& S, const Epi& E) {
;     const int tid = my_tid(), wid = __builtin_amdgcn_readfirstlane(tid >> 6), lane = tid & 63, wr = wid >> 2, wc = wid & 3, fr = lane & 15, fq = lane >> 4;
;     const int nt = g.K / BK;
;     unsigned voffA[2], voffB[2];
; #pragma unroll
;     for (int i = 0; i < 2; ++i) { int R, C; stage_rc(tid * 16 + i * 8192, R, C); const int Rb = Epi::PERM ? ((R & ~31) + perm32(R & 31)) : R;
;         voffA[i] = (unsigned)(R * g.lda + C) * 2u; voffB[i] = (unsigned)(Rb * g.ldb + C) * 2u; }
;     const size_t kstep = (size_t)(BK * 2);
;     const size_t hA = (size_t)HALF * g.lda * 2, hB = (size_t)HALF * g.ldb * 2;
;     const size_t tA = 2 * hA, tB = 2 * hB;
;     const unsigned ldsw = (unsigned)wid * 1024u;
;     const int aoff = lds_byte(wr * 64 + fr, fq * 8), boff = lds_byte(wc * 32 + fr, fq * 8);
;     ...
;     const char* cA = (const char*)g.A + (size_t)cur.pm * tA + (size_t)cur.pn * g.acol; const char* cB = (const char*)g.Bt + (size_t)cur.pn * tB;
;     PG8_STAGE(PG8_SB(0, 0), cB, voffB); PG8_STAGE(PG8_SB(0, 1), cB + hB, voffB); PG8_STAGE(PG8_SA(0, 0), cA, voffA); PG8_STAGE(PG8_SA(0, 1), cA + hA, voffA);
;     if (wr == 1) PG8_BAR;
;     PG8_WAIT_V(2); PG8_BAR;
;     PG8_STAGE(PG8_SB(1, 0), cB + kstep, voffB); PG8_STAGE(PG8_SA(1, 0), cA + kstep, voffA); PG8_STAGE(PG8_SB(1, 1), cB + hB + kstep, voffB);
;     PG8_WAIT_V(6); PG8_BAR;
.LBB0_992:
	s_andn2_b64 vcc, exec, s[6:7]
	s_cbranch_vccnz .LBB0_1028
	s_waitcnt lgkmcnt(0)
	v_ashrrev_i32_e32 v1, 31, v8
	v_lshrrev_b32_e32 v1, 26, v1
	v_add_u32_e32 v1, v8, v1
	s_waitcnt vmcnt(0)
	v_ashrrev_i32_e32 v9, 6, v1
	v_bfe_i32 v1, v8, 27, 1
	v_lshlrev_b32_e32 v0, 4, v8
	v_lshrrev_b32_e32 v1, 22, v1
	v_add_u32_e32 v1, v0, v1
	v_and_b32_e32 v1, 0xfffffc00, v1
	v_sub_u32_e32 v1, v0, v1
	v_lshrrev_b32_e32 v2, 4, v1
	v_bitop3_b32 v2, v2, v1, 32 bitop3:0x6c
	v_ashrrev_i32_e32 v1, 31, v1
	v_lshrrev_b32_e32 v1, 26, v1
	v_add_u32_e32 v1, v2, v1
	v_ashrrev_i32_e32 v10, 6, v1
	v_lshlrev_b32_e32 v3, 3, v9
	v_mul_i32_i24_e32 v4, 64, v10
	v_and_b32_e32 v3, -16, v3
	v_sub_u32_e32 v2, v2, v4
	v_mov_b32_e32 v4, 1
	v_add_u32_e32 v1, v10, v3
	v_lshlrev_b32_e32 v3, 5, v9
	v_ashrrev_i16_sdwa v2, v4, sext(v2) dst_sel:DWORD dst_unused:UNUSED_PAD src0_sel:DWORD src1_sel:BYTE_0
	v_and_b32_e32 v3, 32, v3
	v_bfe_i32 v11, v2, 0, 16
	v_and_b32_e32 v6, 3, v10
	s_mov_b32 s7, 0x3ffe0
	v_add_lshl_u32 v3, v3, v11, 1
	v_add_u32_e32 v0, 0x2000, v0
	v_lshlrev_b32_e32 v2, 1, v1
	v_lshrrev_b32_e32 v5, 2, v1
	v_and_or_b32 v6, v1, s7, v6
	v_lshl_add_u32 v144, v1, 14, v3
	v_ashrrev_i32_e32 v1, 31, v0
	v_lshrrev_b32_e32 v1, 22, v1
	v_add_u32_e32 v1, v0, v1
	v_ashrrev_i32_e32 v12, 10, v1
	v_mul_i32_i24_e32 v1, 0x400, v12
	v_sub_u32_e32 v0, v0, v1
	s_load_dwordx2 s[4:5], s[4:5], 0xe0
	v_and_b32_e32 v2, 24, v2
	v_and_b32_e32 v5, 4, v5
	v_lshrrev_b32_e32 v1, 4, v0
	v_or3_b32 v2, v6, v5, v2
	v_bitop3_b32 v0, v1, v0, 32 bitop3:0x6c
	v_lshl_add_u32 v146, v2, 14, v3
	v_ashrrev_i32_e32 v2, 31, v0
	v_lshrrev_b32_e32 v2, 26, v2
	v_add_u32_e32 v2, v0, v2
	s_waitcnt lgkmcnt(0)
	s_add_u32 s0, s4, 0x6000000
	v_lshlrev_b32_e32 v1, 3, v12
	v_ashrrev_i32_e32 v13, 6, v2
	v_and_b32_e32 v2, 0xc0, v2
	s_addc_u32 s1, s5, 0
	v_and_b32_e32 v1, -16, v1
	v_sub_u32_e32 v0, v0, v2
	s_add_u32 s2, s4, 0x10000000
	v_add_u32_e32 v1, v13, v1
	v_ashrrev_i16_sdwa v0, v4, sext(v0) dst_sel:DWORD dst_unused:UNUSED_PAD src0_sel:DWORD src1_sel:BYTE_0
	v_and_b32_e32 v4, 3, v13
	s_addc_u32 s3, s5, 0
	v_and_or_b32 v4, v1, s7, v4
	s_ashr_i32 s7, s18, 6
	s_ashr_i32 s31, s30, 31
	s_ashr_i32 s35, s34, 31
	s_ashr_i32 s6, s18, 8
	s_lshl_b32 s33, s7, 10
	s_lshl_b64 s[10:11], s[30:31], 22
	s_lshl_b64 s[12:13], s[34:35], 22
	s_add_u32 s40, s0, s12
	v_lshlrev_b32_e32 v3, 5, v12
	v_bfe_i32 v14, v0, 0, 16
	v_lshlrev_b32_e32 v0, 1, v1
	v_lshrrev_b32_e32 v2, 2, v1
	s_addc_u32 s41, s1, s13
	s_add_i32 s35, s33, 0
	v_and_b32_e32 v3, 32, v3
	v_and_b32_e32 v0, 24, v0
	v_and_b32_e32 v2, 4, v2
	s_add_i32 m0, s35, 0x10000
	v_or3_b32 v0, v4, v2, v0
	v_add_lshl_u32 v2, v3, v14, 1
	global_load_lds_dwordx4 v146, s[40:41]
	s_add_i32 m0, s35, 0x12000
	v_lshl_add_u32 v150, v0, 14, v2
	s_add_u32 s12, s40, 0x200000
	global_load_lds_dwordx4 v150, s[40:41]
	s_addc_u32 s13, s41, 0
	s_add_i32 m0, s35, 0x14000
	v_lshl_add_u32 v148, v1, 14, v2
	global_load_lds_dwordx4 v146, s[12:13]
	s_add_i32 m0, s35, 0x16000
	s_add_u32 s36, s2, s10
	s_addc_u32 s37, s3, s11
	s_add_i32 s38, s35, 0x2000
	global_load_lds_dwordx4 v150, s[12:13]
	s_mov_b32 m0, s35
	s_add_u32 s10, s36, 0x200000
	global_load_lds_dwordx4 v144, s[36:37]
	s_mov_b32 m0, s38
	s_addc_u32 s11, s37, 0
	s_add_i32 s39, s35, 0x4000
	global_load_lds_dwordx4 v148, s[36:37]
	s_mov_b32 m0, s39
	s_add_i32 s44, s35, 0x6000
	global_load_lds_dwordx4 v144, s[10:11]
	s_mov_b32 m0, s44
	v_mov_b32_e32 v147, 0
	global_load_lds_dwordx4 v148, s[10:11]
	v_mov_b32_e32 v151, v147
	v_mov_b32_e32 v145, v147
	v_mov_b32_e32 v149, v147
	s_cmp_eq_u32 s6, 1
	s_mov_b32 s45, 0
	v_lshl_add_u64 v[6:7], s[40:41], 0, v[146:147]
	v_lshl_add_u64 v[4:5], s[40:41], 0, v[150:151]
	v_lshl_add_u64 v[0:1], s[36:37], 0, v[144:145]
	s_cselect_b64 s[10:11], -1, 0
	s_cmp_lg_u32 s6, 1
	v_lshl_add_u64 v[2:3], s[36:37], 0, v[148:149]
	s_cbranch_scc1 .LBB0_995
	s_nop 0
.LBB0_995:
	s_ashr_i32 s46, s76, 31
	s_ashr_i32 s47, s84, 31
	s_add_u32 s12, s4, 0xc000000
	s_addc_u32 s13, s5, 0
	s_add_u32 s14, s4, 0x60000
	s_addc_u32 s15, s5, 0
	s_lshl_b32 s4, s7, 5
	s_mov_b64 s[16:17], 0x80
	s_and_b32 s7, s4, 0x60
	s_add_i32 m0, s35, 0x18000
	v_lshl_add_u64 v[6:7], v[6:7], 0, s[16:17]
	s_lshl_b32 s19, s6, 13
	s_lshl_b32 s20, s7, 7
	global_load_lds_dwordx4 v[6:7], off
	v_lshl_add_u64 v[4:5], v[4:5], 0, s[16:17]
	s_add_i32 m0, s35, 0x1a000
	s_add_i32 s48, s35, 0x8000
	s_add_i32 s49, s35, 0xa000
	global_load_lds_dwordx4 v[4:5], off
	v_lshl_add_u64 v[0:1], v[0:1], 0, s[16:17]
	s_mov_b32 m0, s48
	s_add_u32 s4, s40, 0x200080
	global_load_lds_dwordx4 v[0:1], off
	v_lshl_add_u64 v[0:1], v[2:3], 0, s[16:17]
	s_mov_b32 m0, s49
	s_addc_u32 s5, s41, 0
	global_load_lds_dwordx4 v[0:1], off
	s_add_i32 m0, s35, 0x1c000
	v_lshl_add_u64 v[0:1], s[4:5], 0, v[146:147]
	global_load_lds_dwordx4 v[0:1], off
	v_lshl_add_u64 v[0:1], s[4:5], 0, v[150:151]
	s_add_i32 m0, s35, 0x1e000
	s_cmpk_lt_u32 s18, 0x100
	global_load_lds_dwordx4 v[0:1], off
	s_cselect_b32 s97, 1, 0
	v_readfirstlane_b32 s101, v193
	s_nop 3
	s_lshr_b32 s101, s101, 6
	s_cmp_lt_u32 s101, 4
	s_cbranch_scc1 .Lpro_skip_7
	s_barrier
.Lpro_skip_7:
	s_waitcnt vmcnt(8)
	s_barrier
	s_cmp_lg_u32 s97, 0
	v_bfe_u32 v0, v8, 4, 2
	v_and_b32_e32 v1, 15, v8
	v_lshlrev_b32_e32 v2, 4, v0
	v_lshl_or_b32 v172, s6, 6, v1
	v_lshl_or_b32 v1, v1, 6, v2
	v_lshlrev_b32_e32 v2, 2, v8
	v_cmp_eq_u32_e64 s[4:5], 0, v0
	v_lshl_or_b32 v174, v0, 3, s7
	v_lshlrev_b32_e32 v0, 17, v9
	v_and_b32_e32 v2, 32, v2
	v_and_b32_e32 v0, 0xfffc0000, v0
	v_bitop3_b32 v3, v1, s19, v2 bitop3:0xde
	v_bitop3_b32 v173, v1, s20, v2 bitop3:0xde
	v_lshl_add_u32 v0, v10, 14, v0
	v_and_b32_e32 v1, 1, v9
	v_lshl_or_b32 v0, v1, 6, v0
	v_lshl_add_u32 v152, v11, 1, v0
	v_lshlrev_b32_e32 v0, 17, v12
	v_and_b32_e32 v0, 0xfffc0000, v0
	v_lshl_add_u32 v0, v13, 14, v0
	v_and_b32_e32 v1, 1, v12
	s_waitcnt vmcnt(6)
	v_lshl_or_b32 v0, v1, 6, v0
	s_cselect_b64 s[18:19], -1, 0
	v_lshl_add_u32 v154, v14, 1, v0
	s_add_i32 s51, 0, 0x10000
	s_add_i32 s52, 0, 0x14000
	v_mbcnt_lo_u32_b32 v0, -1, 0
	s_mov_b32 s50, s76
	v_mov_b32_e32 v153, v147
	v_mov_b32_e32 v155, v147
	v_mov_b64_e32 v[156:157], 0x200
	v_mov_b64_e32 v[158:159], 0x1ff
	v_add_u32_e32 v175, s51, v173
	v_add_u32_e32 v176, s52, v173
	v_add_u32_e32 v177, 0, v3
	s_mov_b64 s[20:21], 0x80000
	s_mov_b32 s53, 0x80000
	v_mbcnt_hi_u32_b32 v178, -1, v0
	s_barrier
	s_branch .LBB0_998

; __device__ __forceinline__ int my_tid() { int t = threadIdx.x; asm volatile("" : "+v"(t)); return t; }
; #define PG8_STAGE(bufoff, gbase, voff) do { _Pragma("unroll") for (int _i = 0; _i < 2; ++_i) \
;         __builtin_amdgcn_global_load_lds((const unsigned*)((const char*)(gbase) + (voff)[_i]), (LAS unsigned*)(lds + (bufoff) + ldsw + _i * 8192), 16, 0, 0); } while (0)
; #define PG8_BAR __builtin_amdgcn_s_barrier()
; template <class Epi, bool ALIGN_EPI>
; __device__ __forceinline__ void gemm_phase(LAS unsigned char* lds, const Gemm g, const StaticOrder& S, const Epi& E) {
;     const int tid = my_tid(), wid = __builtin_amdgcn_readfirstlane(tid >> 6), lane = tid & 63, wr = wid >> 2, wc = wid & 3, fr = lane & 15, fq = lane >> 4;
;     const int nt = g.K / BK;
;     unsigned voffA[2], voffB[2];
; #pragma unroll
;     for (int i = 0; i < 2; ++i) { int R, C; stage_rc(tid * 16 + i * 8192, R, C); const int Rb = Epi::PERM ? ((R & ~31) + perm32(R & 31)) : R;
;         voffA[i] = (unsigned)(R * g.lda + C) * 2u; voffB[i] = (unsigned)(Rb * g.ldb + C) * 2u; }
;     const size_t kstep = (size_t)(BK * 2);
;     const size_t hA = (size_t)HALF * g.lda * 2, hB = (size_t)HALF * g.ldb * 2;
;     const size_t tA = 2 * hA, tB = 2 * hB;
;     const unsigned ldsw = (unsigned)wid * 1024u;
;     const int aoff = lds_byte(wr * 64 + fr, fq * 8), boff = lds_byte(wc * 32 + fr, fq * 8);
;     ...
;     const char* cA = (const char*)g.A + (size_t)cur.pm * tA + (size_t)cur.pn * g.acol; const char* cB = (const char*)g.Bt + (size_t)cur.pn * tB;
;     PG8_STAGE(PG8_SB(0, 0), cB, voffB); PG8_STAGE(PG8_SB(0, 1), cB + hB, voffB); PG8_STAGE(PG8_SA(0, 0), cA, voffA); PG8_STAGE(PG8_SA(0, 1), cA + hA, voffA);
;     if (wr == 1) PG8_BAR;
.LBB0_1085:
	s_andn2_b64 vcc, exec, s[6:7]
	s_cbranch_vccnz .LBB0_1142
	s_waitcnt lgkmcnt(0)
	v_ashrrev_i32_e32 v1, 31, v8
	v_lshrrev_b32_e32 v1, 26, v1
	v_add_u32_e32 v1, v8, v1
	s_waitcnt vmcnt(0)
	v_ashrrev_i32_e32 v9, 6, v1
	v_bfe_i32 v1, v8, 27, 1
	v_lshlrev_b32_e32 v0, 4, v8
	v_lshrrev_b32_e32 v1, 22, v1
	v_add_u32_e32 v1, v0, v1
	v_and_b32_e32 v1, 0xfffffc00, v1
	v_sub_u32_e32 v1, v0, v1
	v_lshrrev_b32_e32 v2, 4, v1
	v_bitop3_b32 v2, v2, v1, 32 bitop3:0x6c
	v_ashrrev_i32_e32 v1, 31, v1
	v_lshrrev_b32_e32 v1, 26, v1
	v_add_u32_e32 v1, v2, v1
	v_ashrrev_i32_e32 v10, 6, v1
	v_lshlrev_b32_e32 v3, 3, v9
	v_mul_i32_i24_e32 v4, 64, v10
	v_and_b32_e32 v3, -16, v3
	v_sub_u32_e32 v2, v2, v4
	v_mov_b32_e32 v4, 1
	v_add_u32_e32 v1, v10, v3
	v_lshlrev_b32_e32 v3, 5, v9
	v_ashrrev_i16_sdwa v2, v4, sext(v2) dst_sel:DWORD dst_unused:UNUSED_PAD src0_sel:DWORD src1_sel:BYTE_0
	v_and_b32_e32 v3, 32, v3
	v_bfe_i32 v11, v2, 0, 16
	v_and_b32_e32 v6, 3, v10
	s_mov_b32 s2, 0xfffe0
	v_add_lshl_u32 v3, v3, v11, 1
	v_add_u32_e32 v0, 0x2000, v0
	v_lshlrev_b32_e32 v2, 1, v1
	v_lshrrev_b32_e32 v5, 2, v1
	v_and_or_b32 v6, v1, s2, v6
	v_lshl_add_u32 v128, v1, 12, v3
	v_ashrrev_i32_e32 v1, 31, v0
	v_lshrrev_b32_e32 v1, 22, v1
	v_add_u32_e32 v1, v0, v1
	v_ashrrev_i32_e32 v12, 10, v1
	s_load_dwordx2 s[6:7], s[4:5], 0xe0
	v_mul_i32_i24_e32 v1, 0x400, v12
	v_sub_u32_e32 v0, v0, v1
	v_and_b32_e32 v2, 24, v2
	v_and_b32_e32 v5, 4, v5
	v_lshrrev_b32_e32 v1, 4, v0
	v_or3_b32 v2, v6, v5, v2
	v_bitop3_b32 v0, v1, v0, 32 bitop3:0x6c
	v_lshl_add_u32 v130, v2, 12, v3
	v_ashrrev_i32_e32 v2, 31, v0
	s_waitcnt lgkmcnt(0)
	s_add_u32 s33, s6, 0x1f60000
	v_lshrrev_b32_e32 v2, 26, v2
	s_addc_u32 s48, s7, 0
	v_add_u32_e32 v2, v0, v2
	s_add_u32 s49, s6, 0xc000000
	v_lshlrev_b32_e32 v1, 3, v12
	v_ashrrev_i32_e32 v13, 6, v2
	v_and_b32_e32 v2, 0xc0, v2
	s_addc_u32 s50, s7, 0
	v_and_b32_e32 v1, -16, v1
	v_sub_u32_e32 v0, v0, v2
	s_add_u32 s10, s6, 0x60000
	v_add_u32_e32 v1, v13, v1
	v_ashrrev_i16_sdwa v0, v4, sext(v0) dst_sel:DWORD dst_unused:UNUSED_PAD src0_sel:DWORD src1_sel:BYTE_0
	s_addc_u32 s11, s7, 0
	s_ashr_i32 s1, s0, 8
	v_lshlrev_b32_e32 v3, 5, v12
	v_bfe_i32 v14, v0, 0, 16
	v_lshlrev_b32_e32 v0, 1, v1
	v_lshrrev_b32_e32 v2, 2, v1
	v_and_b32_e32 v4, 3, v13
	v_and_b32_e32 v3, 32, v3
	v_and_b32_e32 v0, 24, v0
	v_and_b32_e32 v2, 4, v2
	v_and_or_b32 v4, v1, s2, v4
	s_lshl_b32 s2, s1, 6
	s_lshl_b32 s4, s40, 8
	v_or3_b32 v0, v4, v2, v0
	v_add_lshl_u32 v2, v3, v14, 1
	s_ashr_i32 s3, s0, 6
	v_and_b32_e32 v15, 15, v8
	s_add_i32 s4, s4, s2
	s_ashr_i32 s41, s40, 31
	s_ashr_i32 s43, s42, 31
	v_lshl_add_u32 v134, v0, 12, v2
	s_lshl_b32 s51, s3, 10
	v_or_b32_e32 v0, s4, v15
	s_lshl_b64 s[4:5], s[40:41], 20
	s_lshl_b64 s[12:13], s[42:43], 20
	s_add_u32 s36, s33, s12
	v_lshl_add_u32 v132, v1, 12, v2
	v_ashrrev_i32_e32 v1, 31, v0
	s_addc_u32 s37, s48, s13
	s_add_i32 s41, s51, 0
	v_lshl_add_u64 v[0:1], v[0:1], 2, s[10:11]
	s_add_i32 m0, s41, 0x10000
	global_load_dword v144, v[0:1], off
	global_load_dword v172, v[0:1], off offset:64
	global_load_dword v171, v[0:1], off offset:128
	global_load_dword v170, v[0:1], off offset:192
	global_load_dword v169, v[0:1], off offset:512
	global_load_dword v167, v[0:1], off offset:576
	global_load_dword v166, v[0:1], off offset:640
	global_load_dword v165, v[0:1], off offset:704
	v_mov_b32_e32 v131, 0
	global_load_lds_dwordx4 v130, s[36:37]
	s_add_i32 m0, s41, 0x12000
	s_add_u32 s12, s36, 0x80000
	global_load_lds_dwordx4 v134, s[36:37]
	s_addc_u32 s13, s37, 0
	s_add_i32 m0, s41, 0x14000
	v_mov_b32_e32 v135, v131
	global_load_lds_dwordx4 v130, s[12:13]
	s_add_i32 m0, s41, 0x16000
	s_add_u32 s4, s49, s4
	s_addc_u32 s5, s50, s5
	s_add_i32 s43, s41, 0x2000
	global_load_lds_dwordx4 v134, s[12:13]
	s_mov_b32 m0, s41
	s_add_u32 s12, s4, 0x80000
	global_load_lds_dwordx4 v128, s[4:5]
	s_mov_b32 m0, s43
	s_addc_u32 s13, s5, 0
	s_add_i32 s52, s41, 0x4000
	global_load_lds_dwordx4 v132, s[4:5]
	s_mov_b32 m0, s52
	s_add_i32 s53, s41, 0x6000
	global_load_lds_dwordx4 v128, s[12:13]
	s_mov_b32 m0, s53
	v_mov_b32_e32 v129, v131
	global_load_lds_dwordx4 v132, s[12:13]
	v_mov_b32_e32 v133, v131
	s_cmp_eq_u32 s1, 1
	s_mov_b32 s54, 0
	v_lshl_add_u64 v[6:7], s[36:37], 0, v[130:131]
	v_lshl_add_u64 v[4:5], s[36:37], 0, v[134:135]
	v_lshl_add_u64 v[0:1], s[4:5], 0, v[128:129]
	s_cselect_b64 s[12:13], -1, 0
	s_cmp_lg_u32 s1, 1
	v_lshl_add_u64 v[2:3], s[4:5], 0, v[132:133]
	s_cbranch_scc1 .LBB0_1088
	s_nop 0
; #define PG8_STAGE(bufoff, gbase, voff) do { _Pragma("unroll") for (int _i = 0; _i < 2; ++_i) \
;         __builtin_amdgcn_global_load_lds((const unsigned*)((const char*)(gbase) + (voff)[_i]), (LAS unsigned*)(lds + (bufoff) + ldsw + _i * 8192), 16, 0, 0); } while (0)
; #define PG8_WAIT_V(n) asm volatile("s_waitcnt vmcnt(" #n ")" ::: "memory")
; #define PG8_BAR __builtin_amdgcn_s_barrier()
; template <class Epi, bool ALIGN_EPI>
; __device__ __forceinline__ void gemm_phase(LAS unsigned char* lds, const Gemm g, const StaticOrder& S, const Epi& E) {
;     ...
;     PG8_STAGE(PG8_SB(1, 0), cB + kstep, voffB); PG8_STAGE(PG8_SA(1, 0), cA + kstep, voffA); PG8_STAGE(PG8_SB(1, 1), cB + hB + kstep, voffB);
;     PG8_WAIT_V(6); PG8_BAR;
.LBB0_1088:
	s_ashr_i32 s55, s76, 31
	s_ashr_i32 s56, s84, 31
	s_add_u32 s14, s6, 0x10000000
	s_addc_u32 s15, s7, 0
	s_add_u32 s16, s6, 0x13000000
	s_addc_u32 s17, s7, 0
	s_add_u32 s18, s6, 0x16000000
	s_addc_u32 s19, s7, 0
	s_lshl_b32 s3, s3, 5
	s_mov_b64 s[20:21], 0x80
	s_and_b32 s3, s3, 0x60
	s_add_i32 m0, s41, 0x18000
	v_lshl_add_u64 v[6:7], v[6:7], 0, s[20:21]
	s_lshl_b32 s1, s1, 13
	s_lshl_b32 s22, s3, 7
	global_load_lds_dwordx4 v[6:7], off
	v_lshl_add_u64 v[4:5], v[4:5], 0, s[20:21]
	s_add_i32 m0, s41, 0x1a000
	s_add_i32 s57, s41, 0x8000
	s_add_i32 s58, s41, 0xa000
	global_load_lds_dwordx4 v[4:5], off
	v_lshl_add_u64 v[0:1], v[0:1], 0, s[20:21]
	s_mov_b32 m0, s57
	s_add_u32 s6, s36, 0x80080
	global_load_lds_dwordx4 v[0:1], off
	v_lshl_add_u64 v[0:1], v[2:3], 0, s[20:21]
	s_mov_b32 m0, s58
	s_addc_u32 s7, s37, 0
	global_load_lds_dwordx4 v[0:1], off
	s_add_i32 m0, s41, 0x1c000
	v_lshl_add_u64 v[0:1], s[6:7], 0, v[130:131]
	global_load_lds_dwordx4 v[0:1], off
	v_lshl_add_u64 v[0:1], s[6:7], 0, v[134:135]
	s_add_i32 m0, s41, 0x1e000
	v_or_b32_e32 v150, s2, v15
	global_load_lds_dwordx4 v[0:1], off
	s_cselect_b32 s97, 1, 0
	v_readfirstlane_b32 s101, v193
	s_nop 3
	s_lshr_b32 s101, s101, 6
	s_cmp_lt_u32 s101, 4
	s_cbranch_scc1 .Lpro_skip_8
	s_barrier
.Lpro_skip_8:
	s_waitcnt vmcnt(8)
	s_barrier
	s_cmp_lg_u32 s97, 0
	v_lshrrev_b32_e32 v0, 1, v8
	v_and_b32_e32 v0, 24, v0
	v_lshlrev_b32_e32 v1, 6, v150
	v_lshlrev_b32_e32 v2, 1, v0
	s_movk_i32 s2, 0x3c0
	v_lshlrev_b32_e32 v3, 2, v150
	v_and_or_b32 v1, v1, s2, v2
	v_and_b32_e32 v3, 32, v3
	v_bitop3_b32 v1, v1, s1, v3 bitop3:0xde
	v_lshlrev_b32_e32 v3, 2, v15
	v_or_b32_e32 v152, s3, v0
	v_lshlrev_b32_e32 v0, 15, v9
	v_lshl_or_b32 v2, v15, 6, v2
	v_and_b32_e32 v3, 32, v3
	v_and_b32_e32 v0, 0xffff0000, v0
	v_bitop3_b32 v151, v2, s22, v3 bitop3:0xde
	v_lshl_add_u32 v0, v10, 12, v0
	v_and_b32_e32 v2, 1, v9
	v_lshl_or_b32 v0, v2, 6, v0
	v_lshl_add_u32 v136, v11, 1, v0
	v_lshlrev_b32_e32 v0, 15, v12
	v_and_b32_e32 v0, 0xffff0000, v0
	s_waitcnt vmcnt(6)
	s_cmpk_lt_u32 s0, 0x100
	v_lshl_add_u32 v0, v13, 12, v0
	v_and_b32_e32 v2, 1, v12
	s_cselect_b64 s[22:23], -1, 0
	v_lshl_or_b32 v0, v2, 6, v0
	s_add_i32 s61, 0, 0x10000
	s_add_i32 s62, 0, 0x14000
	s_mov_b32 s59, s76
	v_mov_b32_e32 v137, v131
	v_lshl_add_u32 v138, v14, 1, v0
	v_mov_b32_e32 v139, v131
	v_mov_b64_e32 v[140:141], 0x380
	v_mov_b64_e32 v[142:143], 0x37f
	s_movk_i32 s60, 0x71
	s_mov_b64 s[24:25], 0x100
	v_add_u32_e32 v153, s61, v151
	v_add_u32_e32 v154, s62, v151
	v_add_u32_e32 v155, 0, v1
	v_mov_b32_e32 v156, 0x358637bd
	s_mov_b32 s63, 0x800000
	s_barrier
	s_branch .LBB0_1091

; __device__ __forceinline__ int my_tid() { int t = threadIdx.x; asm volatile("" : "+v"(t)); return t; }
; #define PG8_STAGE(bufoff, gbase, voff) do { _Pragma("unroll") for (int _i = 0; _i < 2; ++_i) \
;         __builtin_amdgcn_global_load_lds((const unsigned*)((const char*)(gbase) + (voff)[_i]), (LAS unsigned*)(lds + (bufoff) + ldsw + _i * 8192), 16, 0, 0); } while (0)
; #define PG8_WAIT_V(n) asm volatile("s_waitcnt vmcnt(" #n ")" ::: "memory")
; #define PG8_BAR __builtin_amdgcn_s_barrier()
; template <class Epi, bool ALIGN_EPI>
; __device__ __forceinline__ void gemm_phase(LAS unsigned char* lds, const Gemm g, const StaticOrder& S, const Epi& E) {
;     const int tid = my_tid(), wid = __builtin_amdgcn_readfirstlane(tid >> 6), lane = tid & 63, wr = wid >> 2, wc = wid & 3, fr = lane & 15, fq = lane >> 4;
;     const int nt = g.K / BK;
;     unsigned voffA[2], voffB[2];
; #pragma unroll
;     for (int i = 0; i < 2; ++i) { int R, C; stage_rc(tid * 16 + i * 8192, R, C); const int Rb = Epi::PERM ? ((R & ~31) + perm32(R & 31)) : R;
;         voffA[i] = (unsigned)(R * g.lda + C) * 2u; voffB[i] = (unsigned)(Rb * g.ldb + C) * 2u; }
;     const size_t kstep = (size_t)(BK * 2);
;     const size_t hA = (size_t)HALF * g.lda * 2, hB = (size_t)HALF * g.ldb * 2;
;     const size_t tA = 2 * hA, tB = 2 * hB;
;     const unsigned ldsw = (unsigned)wid * 1024u;
;     const int aoff = lds_byte(wr * 64 + fr, fq * 8), boff = lds_byte(wc * 32 + fr, fq * 8);
;     ...
;     const char* cA = (const char*)g.A + (size_t)cur.pm * tA + (size_t)cur.pn * g.acol; const char* cB = (const char*)g.Bt + (size_t)cur.pn * tB;
;     PG8_STAGE(PG8_SB(0, 0), cB, voffB); PG8_STAGE(PG8_SB(0, 1), cB + hB, voffB); PG8_STAGE(PG8_SA(0, 0), cA, voffA); PG8_STAGE(PG8_SA(0, 1), cA + hA, voffA);
;     if (wr == 1) PG8_BAR;
;     PG8_WAIT_V(2); PG8_BAR;
;     PG8_STAGE(PG8_SB(1, 0), cB + kstep, voffB); PG8_STAGE(PG8_SA(1, 0), cA + kstep, voffA); PG8_STAGE(PG8_SB(1, 1), cB + hB + kstep, voffB);
;     PG8_WAIT_V(6); PG8_BAR;
.LBB0_1572:
	s_andn2_b64 vcc, exec, s[6:7]
	s_cbranch_vccnz .LBB0_1608
	s_waitcnt lgkmcnt(0)
	v_ashrrev_i32_e32 v1, 31, v8
	v_lshrrev_b32_e32 v1, 26, v1
	v_add_u32_e32 v1, v8, v1
	v_ashrrev_i32_e32 v9, 6, v1
	v_bfe_i32 v1, v8, 27, 1
	v_lshlrev_b32_e32 v0, 4, v8
	v_lshrrev_b32_e32 v1, 22, v1
	v_add_u32_e32 v1, v0, v1
	v_and_b32_e32 v1, 0xfffffc00, v1
	v_sub_u32_e32 v1, v0, v1
	v_lshrrev_b32_e32 v2, 4, v1
	v_bitop3_b32 v2, v2, v1, 32 bitop3:0x6c
	v_ashrrev_i32_e32 v1, 31, v1
	v_lshrrev_b32_e32 v1, 26, v1
	v_add_u32_e32 v1, v2, v1
	v_ashrrev_i32_e32 v10, 6, v1
	v_lshlrev_b32_e32 v3, 3, v9
	v_mul_i32_i24_e32 v4, 64, v10
	v_and_b32_e32 v3, -16, v3
	v_sub_u32_e32 v2, v2, v4
	v_mov_b32_e32 v4, 1
	v_add_u32_e32 v1, v10, v3
	v_lshlrev_b32_e32 v3, 5, v9
	v_ashrrev_i16_sdwa v2, v4, sext(v2) dst_sel:DWORD dst_unused:UNUSED_PAD src0_sel:DWORD src1_sel:BYTE_0
	v_and_b32_e32 v3, 32, v3
	v_bfe_i32 v11, v2, 0, 16
	v_and_b32_e32 v6, 3, v10
	s_mov_b32 s7, 0xfffe0
	v_add_lshl_u32 v3, v3, v11, 1
	v_add_u32_e32 v0, 0x2000, v0
	v_lshlrev_b32_e32 v2, 1, v1
	v_lshrrev_b32_e32 v5, 2, v1
	v_and_or_b32 v6, v1, s7, v6
	v_lshl_add_u32 v144, v1, 12, v3
	v_ashrrev_i32_e32 v1, 31, v0
	v_lshrrev_b32_e32 v1, 22, v1
	v_add_u32_e32 v1, v0, v1
	v_ashrrev_i32_e32 v12, 10, v1
	v_mul_i32_i24_e32 v1, 0x400, v12
	v_sub_u32_e32 v0, v0, v1
	s_load_dwordx2 s[4:5], s[4:5], 0xe0
	v_and_b32_e32 v2, 24, v2
	v_and_b32_e32 v5, 4, v5
	v_lshrrev_b32_e32 v1, 4, v0
	v_or3_b32 v2, v6, v5, v2
	v_bitop3_b32 v0, v1, v0, 32 bitop3:0x6c
	v_lshl_add_u32 v146, v2, 12, v3
	v_ashrrev_i32_e32 v2, 31, v0
	v_lshrrev_b32_e32 v2, 26, v2
	v_add_u32_e32 v2, v0, v2
	s_waitcnt lgkmcnt(0)
	s_add_u32 s0, s4, 0x4000000
	v_lshlrev_b32_e32 v1, 3, v12
	v_ashrrev_i32_e32 v13, 6, v2
	v_and_b32_e32 v2, 0xc0, v2
	s_addc_u32 s1, s5, 0
	v_and_b32_e32 v1, -16, v1
	v_sub_u32_e32 v0, v0, v2
	s_add_u32 s2, s4, 0x1760000
	v_add_u32_e32 v1, v13, v1
	v_ashrrev_i16_sdwa v0, v4, sext(v0) dst_sel:DWORD dst_unused:UNUSED_PAD src0_sel:DWORD src1_sel:BYTE_0
	v_and_b32_e32 v4, 3, v13
	s_addc_u32 s3, s5, 0
	v_and_or_b32 v4, v1, s7, v4
	s_ashr_i32 s7, s20, 6
	s_ashr_i32 s31, s30, 31
	s_ashr_i32 s35, s34, 31
	s_ashr_i32 s6, s20, 8
	s_lshl_b32 s33, s7, 10
	s_lshl_b64 s[10:11], s[30:31], 20
	s_lshl_b64 s[12:13], s[34:35], 20
	s_add_u32 s40, s2, s12
	v_lshlrev_b32_e32 v3, 5, v12
	v_bfe_i32 v14, v0, 0, 16
	v_lshlrev_b32_e32 v0, 1, v1
	v_lshrrev_b32_e32 v2, 2, v1
	s_addc_u32 s41, s3, s13
	s_add_i32 s35, s33, 0
	v_and_b32_e32 v3, 32, v3
	v_and_b32_e32 v0, 24, v0
	v_and_b32_e32 v2, 4, v2
	s_add_i32 m0, s35, 0x10000
	v_or3_b32 v0, v4, v2, v0
	v_add_lshl_u32 v2, v3, v14, 1
	global_load_lds_dwordx4 v146, s[40:41]
	s_add_i32 m0, s35, 0x12000
	v_lshl_add_u32 v150, v0, 12, v2
	s_add_u32 s12, s40, 0x80000
	global_load_lds_dwordx4 v150, s[40:41]
	s_addc_u32 s13, s41, 0
	s_add_i32 m0, s35, 0x14000
	v_lshl_add_u32 v148, v1, 12, v2
	global_load_lds_dwordx4 v146, s[12:13]
	s_add_i32 m0, s35, 0x16000
	s_add_u32 s36, s0, s10
	s_addc_u32 s37, s1, s11
	s_add_i32 s38, s35, 0x2000
	global_load_lds_dwordx4 v150, s[12:13]
	s_mov_b32 m0, s35
	s_add_u32 s10, s36, 0x80000
	global_load_lds_dwordx4 v144, s[36:37]
	s_mov_b32 m0, s38
	s_addc_u32 s11, s37, 0
	s_add_i32 s39, s35, 0x4000
	global_load_lds_dwordx4 v148, s[36:37]
	s_mov_b32 m0, s39
	s_add_i32 s44, s35, 0x6000
	global_load_lds_dwordx4 v144, s[10:11]
	s_mov_b32 m0, s44
	v_mov_b32_e32 v147, 0
	global_load_lds_dwordx4 v148, s[10:11]
	v_mov_b32_e32 v151, v147
	v_mov_b32_e32 v145, v147
	v_mov_b32_e32 v149, v147
	s_cmp_eq_u32 s6, 1
	s_mov_b32 s45, 0
	v_lshl_add_u64 v[6:7], s[40:41], 0, v[146:147]
	v_lshl_add_u64 v[2:3], s[40:41], 0, v[150:151]
	s_mov_b64 s[10:11], 0x80000
	v_lshl_add_u64 v[0:1], s[36:37], 0, v[144:145]
	s_cselect_b64 s[12:13], -1, 0
	s_cmp_lg_u32 s6, 1
	v_lshl_add_u64 v[4:5], s[36:37], 0, v[148:149]
	s_cbranch_scc1 .LBB0_1575
	s_nop 0
.LBB0_1575:
	s_ashr_i32 s46, s76, 31
	s_ashr_i32 s47, s84, 31
	s_add_u32 s14, s4, 0xc000000
	s_addc_u32 s15, s5, 0
	s_add_u32 s16, s4, 0x70000
	s_addc_u32 s17, s5, 0
	s_lshl_b32 s4, s7, 5
	s_mov_b64 s[18:19], 0x80
	s_and_b32 s7, s4, 0x60
	s_add_i32 m0, s35, 0x18000
	v_lshl_add_u64 v[6:7], v[6:7], 0, s[18:19]
	s_lshl_b32 s21, s6, 13
	s_lshl_b32 s22, s7, 7
	global_load_lds_dwordx4 v[6:7], off
	v_lshl_add_u64 v[2:3], v[2:3], 0, s[18:19]
	s_add_i32 m0, s35, 0x1a000
	s_add_i32 s48, s35, 0x8000
	s_add_i32 s49, s35, 0xa000
	global_load_lds_dwordx4 v[2:3], off
	v_lshl_add_u64 v[0:1], v[0:1], 0, s[18:19]
	s_mov_b32 m0, s48
	s_add_u32 s4, s40, 0x80080
	global_load_lds_dwordx4 v[0:1], off
	v_lshl_add_u64 v[0:1], v[4:5], 0, s[18:19]
	s_mov_b32 m0, s49
	s_addc_u32 s5, s41, 0
	global_load_lds_dwordx4 v[0:1], off
	s_add_i32 m0, s35, 0x1c000
	v_lshl_add_u64 v[0:1], s[4:5], 0, v[146:147]
	global_load_lds_dwordx4 v[0:1], off
	v_lshl_add_u64 v[0:1], s[4:5], 0, v[150:151]
	s_add_i32 m0, s35, 0x1e000
	s_cmpk_lt_u32 s20, 0x100
	global_load_lds_dwordx4 v[0:1], off
	s_cselect_b32 s97, 1, 0
	v_readfirstlane_b32 s101, v193
	s_nop 3
	s_lshr_b32 s101, s101, 6
	s_cmp_lt_u32 s101, 4
	s_cbranch_scc1 .Lpro_skip_9
	s_barrier
.Lpro_skip_9:
	s_waitcnt vmcnt(8)
	s_barrier
	s_cmp_lg_u32 s97, 0
	v_bfe_u32 v0, v8, 4, 2
	v_and_b32_e32 v1, 15, v8
	v_lshlrev_b32_e32 v2, 4, v0
	v_lshl_or_b32 v172, s6, 6, v1
	v_lshl_or_b32 v1, v1, 6, v2
	v_lshlrev_b32_e32 v2, 2, v8
	v_cmp_eq_u32_e64 s[4:5], 0, v0
	v_lshl_or_b32 v174, v0, 3, s7
	v_lshlrev_b32_e32 v0, 15, v9
	v_and_b32_e32 v2, 32, v2
	v_and_b32_e32 v0, 0xffff0000, v0
	v_bitop3_b32 v3, v1, s21, v2 bitop3:0xde
	v_bitop3_b32 v173, v1, s22, v2 bitop3:0xde
	v_lshl_add_u32 v0, v10, 12, v0
	v_and_b32_e32 v1, 1, v9
	v_lshl_or_b32 v0, v1, 6, v0
	v_lshl_add_u32 v152, v11, 1, v0
	v_lshlrev_b32_e32 v0, 15, v12
	v_and_b32_e32 v0, 0xffff0000, v0
	v_lshl_add_u32 v0, v13, 12, v0
	v_and_b32_e32 v1, 1, v12
	s_waitcnt vmcnt(6)
	v_lshl_or_b32 v0, v1, 6, v0
	s_cselect_b64 s[20:21], -1, 0
	v_lshl_add_u32 v154, v14, 1, v0
	s_add_i32 s51, 0, 0x10000
	s_add_i32 s52, 0, 0x14000
	v_mbcnt_lo_u32_b32 v0, -1, 0
	s_mov_b32 s50, s76
	v_mov_b32_e32 v153, v147
	v_mov_b32_e32 v155, v147
	v_mov_b64_e32 v[156:157], 0x200
	v_mov_b64_e32 v[158:159], 0x1ff
	v_add_u32_e32 v175, s51, v173
	v_add_u32_e32 v176, s52, v173
	v_add_u32_e32 v177, 0, v3
	s_mov_b32 s53, 0x80000
	v_mbcnt_hi_u32_b32 v178, -1, v0
	s_barrier
	s_branch .LBB0_1578

; __device__ __forceinline__ int my_tid() { int t = threadIdx.x; asm volatile("" : "+v"(t)); return t; }
; #define PG8_STAGE(bufoff, gbase, voff) do { _Pragma("unroll") for (int _i = 0; _i < 2; ++_i) \
;         __builtin_amdgcn_global_load_lds((const unsigned*)((const char*)(gbase) + (voff)[_i]), (LAS unsigned*)(lds + (bufoff) + ldsw + _i * 8192), 16, 0, 0); } while (0)
; #define PG8_BAR __builtin_amdgcn_s_barrier()
; template <class Epi, bool ALIGN_EPI>
; __device__ __forceinline__ void gemm_phase(LAS unsigned char* lds, const Gemm g, const StaticOrder& S, const Epi& E) {
;     const int tid = my_tid(), wid = __builtin_amdgcn_readfirstlane(tid >> 6), lane = tid & 63, wr = wid >> 2, wc = wid & 3, fr = lane & 15, fq = lane >> 4;
;     const int nt = g.K / BK;
;     unsigned voffA[2], voffB[2];
; #pragma unroll
;     for (int i = 0; i < 2; ++i) { int R, C; stage_rc(tid * 16 + i * 8192, R, C); const int Rb = Epi::PERM ? ((R & ~31) + perm32(R & 31)) : R;
;         voffA[i] = (unsigned)(R * g.lda + C) * 2u; voffB[i] = (unsigned)(Rb * g.ldb + C) * 2u; }
;     const size_t kstep = (size_t)(BK * 2);
;     const size_t hA = (size_t)HALF * g.lda * 2, hB = (size_t)HALF * g.ldb * 2;
;     const size_t tA = 2 * hA, tB = 2 * hB;
;     const unsigned ldsw = (unsigned)wid * 1024u;
;     const int aoff = lds_byte(wr * 64 + fr, fq * 8), boff = lds_byte(wc * 32 + fr, fq * 8);
;     ...
;     const char* cA = (const char*)g.A + (size_t)cur.pm * tA + (size_t)cur.pn * g.acol; const char* cB = (const char*)g.Bt + (size_t)cur.pn * tB;
;     PG8_STAGE(PG8_SB(0, 0), cB, voffB); PG8_STAGE(PG8_SB(0, 1), cB + hB, voffB); PG8_STAGE(PG8_SA(0, 0), cA, voffA); PG8_STAGE(PG8_SA(0, 1), cA + hA, voffA);
;     if (wr == 1) PG8_BAR;
.LBB0_1662:
	s_cmp_lt_i32 s80, 19
	s_cselect_b64 s[10:11], -1, 0
	s_cmp_gt_i32 s81, 18
	s_cselect_b64 s[0:1], -1, 0
	s_and_b64 s[0:1], s[10:11], s[0:1]
	s_andn2_b64 vcc, exec, s[0:1]
	s_cbranch_vccnz .LBB0_1685
	s_mov_b64 s[4:5], s[78:79]
	v_mov_b32_e32 v0, v193
	s_waitcnt vmcnt(0)
	v_mov_b32_e32 v8, v193
	s_cmpk_gt_i32 s84, 0x7ff
	s_nop 0
	v_readfirstlane_b32 s21, v8
	s_cbranch_scc1 .LBB0_1685
	v_lshlrev_b32_e32 v0, 4, v8
	s_waitcnt lgkmcnt(0)
	v_add_u32_e32 v1, 0x2000, v0
	v_ashrrev_i32_e32 v2, 31, v1
	v_lshrrev_b32_e32 v2, 22, v2
	v_add_u32_e32 v2, v1, v2
	v_ashrrev_i32_e32 v9, 10, v2
	v_mul_i32_i24_e32 v2, 0x400, v9
	v_sub_u32_e32 v1, v1, v2
	v_lshrrev_b32_e32 v2, 4, v1
	v_bitop3_b32 v1, v2, v1, 32 bitop3:0x6c
	v_ashrrev_i32_e32 v2, 31, v1
	v_lshrrev_b32_e32 v2, 26, v2
	v_add_u32_e32 v2, v1, v2
	v_lshlrev_b32_e32 v3, 3, v9
	v_ashrrev_i32_e32 v11, 6, v2
	v_and_b32_e32 v3, -16, v3
	v_add_u32_e32 v3, v11, v3
	v_and_b32_e32 v4, 3, v11
	s_mov_b32 s6, 0xfffe0
	v_lshrrev_b32_e32 v5, 2, v3
	v_lshlrev_b32_e32 v6, 1, v3
	v_and_b32_e32 v2, 0xc0, v2
	v_and_or_b32 v4, v3, s6, v4
	v_and_b32_e32 v5, 4, v5
	v_and_b32_e32 v6, 24, v6
	v_sub_u32_e32 v1, v1, v2
	v_mov_b32_e32 v2, 1
	v_or3_b32 v4, v4, v5, v6
	v_lshlrev_b32_e32 v5, 5, v9
	v_ashrrev_i16_sdwa v1, v2, sext(v1) dst_sel:DWORD dst_unused:UNUSED_PAD src0_sel:DWORD src1_sel:BYTE_0
	v_and_b32_e32 v5, 32, v5
	v_bfe_i32 v12, v1, 0, 16
	v_add_lshl_u32 v1, v5, v12, 1
	v_lshl_add_u32 v128, v4, 12, v1
	v_lshl_add_u32 v130, v3, 12, v1
	v_bfe_i32 v1, v8, 27, 1
	v_lshrrev_b32_e32 v1, 22, v1
	v_add_u32_e32 v1, v0, v1
	v_and_b32_e32 v1, 0xfffffc00, v1
	v_sub_u32_e32 v0, v0, v1
	s_load_dwordx2 s[4:5], s[4:5], 0xe0
	v_lshrrev_b32_e32 v1, 4, v0
	v_bitop3_b32 v1, v1, v0, 32 bitop3:0x6c
	v_ashrrev_i32_e32 v0, 31, v0
	v_lshrrev_b32_e32 v0, 26, v0
	v_add_u32_e32 v0, v1, v0
	v_ashrrev_i32_e32 v13, 6, v0
	v_ashrrev_i32_e32 v0, 31, v8
	s_waitcnt lgkmcnt(0)
	s_add_u32 s0, s4, 0x8000000
	v_lshrrev_b32_e32 v0, 26, v0
	s_addc_u32 s1, s5, 0
	v_add_u32_e32 v0, v8, v0
	s_add_u32 s2, s4, 0xc000000
	v_ashrrev_i32_e32 v14, 6, v0
	s_addc_u32 s3, s5, 0
	v_lshlrev_b32_e32 v0, 3, v14
	s_add_u32 s12, s4, 0x70000
	v_and_b32_e32 v0, -16, v0
	s_addc_u32 s13, s5, 0
	v_add_u32_e32 v0, v13, v0
	v_and_b32_e32 v3, 3, v13
	s_ashr_i32 s38, s84, 31
	v_and_or_b32 v3, v0, s6, v3
	s_lshr_b32 s6, s38, 29
	s_add_i32 s6, s84, s6
	s_and_b32 s7, s6, -8
	s_ashr_i32 s19, s21, 8
	s_ashr_i32 s18, s21, 6
	s_sub_i32 s7, s84, s7
	s_lshl_b32 s33, s18, 10
	s_lshl_b32 s22, s19, 6
	s_lshl_b32 s9, s7, 8
	s_ashr_i32 s6, s6, 3
	s_mul_i32 s8, s7, 0x101
	s_cmp_lt_i32 s7, 0
	s_cselect_b32 s7, s8, s9
	s_add_i32 s6, s7, s6
	s_ashr_i32 s7, s6, 31
	s_lshr_b32 s7, s7, 25
	s_add_i32 s7, s6, s7
	s_ashr_i32 s8, s7, 7
	s_and_b32 s7, s7, 0xffffff80
	s_sub_i32 s6, s6, s7
	s_bfe_i32 s7, s6, 0x80000
	s_bfe_u32 s7, s7, 0x2000d
	v_lshrrev_b32_e32 v4, 2, v0
	v_lshlrev_b32_e32 v5, 1, v0
	s_add_i32 s7, s6, s7
	v_and_b32_e32 v4, 4, v4
	v_and_b32_e32 v5, 24, v5
	s_bfe_i32 s9, s7, 0x80000
	s_and_b32 s7, s7, 0xfc
	v_or3_b32 v3, v3, v4, v5
	v_mul_i32_i24_e32 v5, 64, v13
	s_sub_i32 s6, s6, s7
	v_sub_u32_e32 v1, v1, v5
	s_lshl_b32 s8, s8, 2
	s_sext_i32_i8 s6, s6
	v_lshlrev_b32_e32 v4, 5, v14
	v_ashrrev_i16_sdwa v1, v2, sext(v1) dst_sel:DWORD dst_unused:UNUSED_PAD src0_sel:DWORD src1_sel:BYTE_0
	s_sext_i32_i16 s9, s9
	s_add_i32 s52, s8, s6
	v_and_b32_e32 v4, 32, v4
	v_bfe_i32 v15, v1, 0, 16
	s_lshr_b32 s20, s9, 2
	s_lshl_b32 s6, s52, 8
	v_and_b32_e32 v10, 15, v8
	v_add_lshl_u32 v1, v4, v15, 1
	s_add_i32 s6, s6, s22
	s_ashr_i32 s53, s52, 31
	s_bfe_i64 s[8:9], s[20:21], 0x100000
	v_lshl_add_u32 v134, v0, 12, v1
	v_or_b32_e32 v0, s6, v10
	s_lshl_b64 s[6:7], s[52:53], 20
	s_lshl_b64 s[8:9], s[8:9], 20
	s_add_u32 s8, s0, s8
	v_lshl_add_u32 v132, v3, 12, v1
	v_ashrrev_i32_e32 v1, 31, v0
	s_addc_u32 s9, s1, s9
	s_add_i32 s39, s33, 0
	v_lshl_add_u64 v[0:1], v[0:1], 2, s[12:13]
	s_add_i32 m0, s39, 0x10000
	global_load_dword v166, v[0:1], off
	global_load_dword v154, v[0:1], off offset:64
	global_load_dword v152, v[0:1], off offset:128
	global_load_dword v150, v[0:1], off offset:192
	global_load_dword v148, v[0:1], off offset:512
	global_load_dword v146, v[0:1], off offset:576
	global_load_dword v145, v[0:1], off offset:640
	global_load_dword v144, v[0:1], off offset:704
	v_mov_b32_e32 v133, 0
	global_load_lds_dwordx4 v132, s[8:9]
	s_add_i32 m0, s39, 0x12000
	s_add_u32 s14, s8, 0x80000
	global_load_lds_dwordx4 v128, s[8:9]
	s_addc_u32 s15, s9, 0
	s_add_i32 m0, s39, 0x14000
	v_mov_b32_e32 v129, v133
	global_load_lds_dwordx4 v132, s[14:15]
	s_add_i32 m0, s39, 0x16000
	s_add_u32 s6, s2, s6
	s_addc_u32 s7, s3, s7
	s_add_i32 s53, s39, 0x2000
	global_load_lds_dwordx4 v128, s[14:15]
	s_mov_b32 m0, s39
	s_add_u32 s14, s6, 0x80000
	global_load_lds_dwordx4 v134, s[6:7]
	s_mov_b32 m0, s53
	s_addc_u32 s15, s7, 0
	s_add_i32 s56, s39, 0x4000
	global_load_lds_dwordx4 v130, s[6:7]
	s_mov_b32 m0, s56
	s_add_i32 s57, s39, 0x6000
	global_load_lds_dwordx4 v134, s[14:15]
	s_mov_b32 m0, s57
	v_mov_b32_e32 v135, v133
	global_load_lds_dwordx4 v130, s[14:15]
	v_mov_b32_e32 v131, v133
	s_cmp_eq_u32 s19, 1
	s_mov_b32 s58, 0
	v_lshl_add_u64 v[6:7], s[8:9], 0, v[132:133]
	v_lshl_add_u64 v[4:5], s[8:9], 0, v[128:129]
	v_lshl_add_u64 v[0:1], s[6:7], 0, v[134:135]
	s_cselect_b64 s[14:15], -1, 0
	s_cmp_lg_u32 s19, 1
	v_lshl_add_u64 v[2:3], s[6:7], 0, v[130:131]
	s_cbranch_scc1 .LBB0_1666
	s_nop 0

; __device__ __forceinline__ int my_tid() { int t = threadIdx.x; asm volatile("" : "+v"(t)); return t; }
; #define PG8_STAGE(bufoff, gbase, voff) do { _Pragma("unroll") for (int _i = 0; _i < 2; ++_i) \
;         __builtin_amdgcn_global_load_lds((const unsigned*)((const char*)(gbase) + (voff)[_i]), (LAS unsigned*)(lds + (bufoff) + ldsw + _i * 8192), 16, 0, 0); } while (0)
; #define PG8_WAIT_V(n) asm volatile("s_waitcnt vmcnt(" #n ")" ::: "memory")
; #define PG8_BAR __builtin_amdgcn_s_barrier()
; template <class Epi, bool ALIGN_EPI>
; __device__ __forceinline__ void gemm_phase(LAS unsigned char* lds, const Gemm g, const StaticOrder& S, const Epi& E) {
;     const int tid = my_tid(), wid = __builtin_amdgcn_readfirstlane(tid >> 6), lane = tid & 63, wr = wid >> 2, wc = wid & 3, fr = lane & 15, fq = lane >> 4;
;     const int nt = g.K / BK;
;     unsigned voffA[2], voffB[2];
; #pragma unroll
;     for (int i = 0; i < 2; ++i) { int R, C; stage_rc(tid * 16 + i * 8192, R, C); const int Rb = Epi::PERM ? ((R & ~31) + perm32(R & 31)) : R;
;         voffA[i] = (unsigned)(R * g.lda + C) * 2u; voffB[i] = (unsigned)(Rb * g.ldb + C) * 2u; }
;     const size_t kstep = (size_t)(BK * 2);
;     const size_t hA = (size_t)HALF * g.lda * 2, hB = (size_t)HALF * g.ldb * 2;
;     const size_t tA = 2 * hA, tB = 2 * hB;
;     const unsigned ldsw = (unsigned)wid * 1024u;
;     const int aoff = lds_byte(wr * 64 + fr, fq * 8), boff = lds_byte(wc * 32 + fr, fq * 8);
;     ...
;     const char* cA = (const char*)g.A + (size_t)cur.pm * tA + (size_t)cur.pn * g.acol; const char* cB = (const char*)g.Bt + (size_t)cur.pn * tB;
;     PG8_STAGE(PG8_SB(0, 0), cB, voffB); PG8_STAGE(PG8_SB(0, 1), cB + hB, voffB); PG8_STAGE(PG8_SA(0, 0), cA, voffA); PG8_STAGE(PG8_SA(0, 1), cA + hA, voffA);
;     if (wr == 1) PG8_BAR;
;     PG8_WAIT_V(2); PG8_BAR;
;     PG8_STAGE(PG8_SB(1, 0), cB + kstep, voffB); PG8_STAGE(PG8_SA(1, 0), cA + kstep, voffA); PG8_STAGE(PG8_SB(1, 1), cB + hB + kstep, voffB);
;     PG8_WAIT_V(6); PG8_BAR;
.LBB0_1742:
	s_andn2_b64 vcc, exec, s[6:7]
	s_cbranch_vccnz .LBB0_1780
	s_waitcnt lgkmcnt(0)
	v_ashrrev_i32_e32 v1, 31, v193
	v_lshrrev_b32_e32 v1, 26, v1
	v_add_u32_e32 v1, v193, v1
	s_waitcnt vmcnt(0)
	v_ashrrev_i32_e32 v8, 6, v1
	v_bfe_i32 v1, v193, 27, 1
	v_lshlrev_b32_e32 v0, 4, v193
	v_lshrrev_b32_e32 v1, 22, v1
	v_add_u32_e32 v1, v0, v1
	v_and_b32_e32 v1, 0xfffffc00, v1
	v_sub_u32_e32 v1, v0, v1
	v_lshrrev_b32_e32 v2, 4, v1
	v_bitop3_b32 v2, v2, v1, 32 bitop3:0x6c
	v_ashrrev_i32_e32 v1, 31, v1
	v_lshrrev_b32_e32 v1, 26, v1
	v_add_u32_e32 v1, v2, v1
	v_ashrrev_i32_e32 v9, 6, v1
	v_lshlrev_b32_e32 v3, 3, v8
	v_mul_i32_i24_e32 v4, 64, v9
	v_and_b32_e32 v3, -16, v3
	v_sub_u32_e32 v2, v2, v4
	v_mov_b32_e32 v4, 1
	v_add_u32_e32 v1, v9, v3
	v_lshlrev_b32_e32 v3, 5, v8
	v_ashrrev_i16_sdwa v2, v4, sext(v2) dst_sel:DWORD dst_unused:UNUSED_PAD src0_sel:DWORD src1_sel:BYTE_0
	v_and_b32_e32 v3, 32, v3
	v_bfe_i32 v10, v2, 0, 16
	v_and_b32_e32 v6, 3, v9
	s_mov_b32 s5, 0x3ffe0
	v_add_lshl_u32 v3, v3, v10, 1
	v_add_u32_e32 v0, 0x2000, v0
	v_lshlrev_b32_e32 v2, 1, v1
	v_lshrrev_b32_e32 v5, 2, v1
	v_and_or_b32 v6, v1, s5, v6
	v_lshl_add_u32 v136, v1, 14, v3
	v_ashrrev_i32_e32 v1, 31, v0
	v_lshrrev_b32_e32 v1, 22, v1
	v_add_u32_e32 v1, v0, v1
	v_ashrrev_i32_e32 v11, 10, v1
	v_mul_i32_i24_e32 v1, 0x400, v11
	v_sub_u32_e32 v0, v0, v1
	s_load_dwordx4 s[8:11], s[78:79], 0xd8
	v_and_b32_e32 v2, 24, v2
	v_and_b32_e32 v5, 4, v5
	v_lshrrev_b32_e32 v1, 4, v0
	v_or3_b32 v2, v6, v5, v2
	v_bitop3_b32 v0, v1, v0, 32 bitop3:0x6c
	v_lshl_add_u32 v138, v2, 14, v3
	v_ashrrev_i32_e32 v2, 31, v0
	v_lshrrev_b32_e32 v2, 26, v2
	v_add_u32_e32 v2, v0, v2
	s_waitcnt lgkmcnt(0)
	s_add_u32 s2, s10, 0xa000000
	v_lshlrev_b32_e32 v1, 3, v11
	v_ashrrev_i32_e32 v12, 6, v2
	v_and_b32_e32 v2, 0xc0, v2
	s_addc_u32 s3, s11, 0
	v_and_b32_e32 v1, -16, v1
	v_sub_u32_e32 v0, v0, v2
	s_add_u32 s33, s10, 0x10000000
	v_add_u32_e32 v1, v12, v1
	v_ashrrev_i16_sdwa v0, v4, sext(v0) dst_sel:DWORD dst_unused:UNUSED_PAD src0_sel:DWORD src1_sel:BYTE_0
	v_and_b32_e32 v4, 3, v12
	s_addc_u32 s36, s11, 0
	v_and_or_b32 v4, v1, s5, v4
	s_ashr_i32 s12, s0, 6
	s_ashr_i32 s5, s4, 31
	s_ashr_i32 s27, s26, 31
	s_ashr_i32 s1, s0, 8
	s_lshl_b32 s37, s12, 10
	s_lshl_b64 s[6:7], s[4:5], 22
	s_lshl_b64 s[14:15], s[26:27], 22
	s_add_u32 s30, s2, s14
	v_lshlrev_b32_e32 v3, 5, v11
	v_bfe_i32 v13, v0, 0, 16
	v_lshlrev_b32_e32 v0, 1, v1
	v_lshrrev_b32_e32 v2, 2, v1
	s_addc_u32 s31, s3, s15
	s_add_i32 s27, s37, 0
	v_and_b32_e32 v3, 32, v3
	v_and_b32_e32 v0, 24, v0
	v_and_b32_e32 v2, 4, v2
	s_add_i32 m0, s27, 0x10000
	v_or3_b32 v0, v4, v2, v0
	v_add_lshl_u32 v2, v3, v13, 1
	global_load_lds_dwordx4 v138, s[30:31]
	s_add_i32 m0, s27, 0x12000
	v_lshl_add_u32 v142, v0, 14, v2
	s_add_u32 s14, s30, 0x200000
	global_load_lds_dwordx4 v142, s[30:31]
	s_addc_u32 s15, s31, 0
	s_add_i32 m0, s27, 0x14000
	v_lshl_add_u32 v140, v1, 14, v2
	global_load_lds_dwordx4 v138, s[14:15]
	s_add_i32 m0, s27, 0x16000
	s_add_u32 s28, s33, s6
	s_addc_u32 s29, s36, s7
	s_add_i32 s38, s27, 0x2000
	global_load_lds_dwordx4 v142, s[14:15]
	s_mov_b32 m0, s27
	s_add_u32 s6, s28, 0x200000
	global_load_lds_dwordx4 v136, s[28:29]
	s_mov_b32 m0, s38
	s_addc_u32 s7, s29, 0
	s_add_i32 s39, s27, 0x4000
	global_load_lds_dwordx4 v140, s[28:29]
	s_mov_b32 m0, s39
	s_add_i32 s40, s27, 0x6000
	global_load_lds_dwordx4 v136, s[6:7]
	s_mov_b32 m0, s40
	v_mov_b32_e32 v139, 0
	global_load_lds_dwordx4 v140, s[6:7]
	v_mov_b32_e32 v143, v139
	v_mov_b32_e32 v137, v139
	v_mov_b32_e32 v141, v139
	s_cmp_eq_u32 s1, 1
	s_mov_b32 s41, 0
	v_lshl_add_u64 v[6:7], s[30:31], 0, v[138:139]
	v_lshl_add_u64 v[4:5], s[30:31], 0, v[142:143]
	v_lshl_add_u64 v[0:1], s[28:29], 0, v[136:137]
	s_cselect_b64 s[6:7], -1, 0
	s_cmp_lg_u32 s1, 1
	v_lshl_add_u64 v[2:3], s[28:29], 0, v[140:141]
	s_cbranch_scc1 .LBB0_1745
	s_nop 0
.LBB0_1745:
	s_ashr_i32 s42, s76, 31
	s_ashr_i32 s43, s84, 31
	s_add_u32 s10, s10, 0xc000000
	s_addc_u32 s11, s11, 0
	s_lshl_b32 s12, s12, 5
	s_and_b32 s18, s12, 0x60
	s_mov_b64 s[12:13], 0x80
	s_add_i32 m0, s27, 0x18000
	v_lshl_add_u64 v[6:7], v[6:7], 0, s[12:13]
	s_lshl_b32 s5, s1, 13
	s_lshl_b32 s16, s18, 7
	global_load_lds_dwordx4 v[6:7], off
	v_lshl_add_u64 v[4:5], v[4:5], 0, s[12:13]
	s_add_i32 m0, s27, 0x1a000
	s_add_i32 s44, s27, 0x8000
	s_add_i32 s45, s27, 0xa000
	global_load_lds_dwordx4 v[4:5], off
	v_lshl_add_u64 v[0:1], v[0:1], 0, s[12:13]
	s_mov_b32 m0, s44
	s_add_u32 s14, s30, 0x200080
	global_load_lds_dwordx4 v[0:1], off
	v_lshl_add_u64 v[0:1], v[2:3], 0, s[12:13]
	s_mov_b32 m0, s45
	s_addc_u32 s15, s31, 0
	global_load_lds_dwordx4 v[0:1], off
	s_add_i32 m0, s27, 0x1c000
	v_lshl_add_u64 v[0:1], s[14:15], 0, v[138:139]
	global_load_lds_dwordx4 v[0:1], off
	v_lshl_add_u64 v[0:1], s[14:15], 0, v[142:143]
	s_add_i32 m0, s27, 0x1e000
	s_cmpk_lt_u32 s0, 0x100
	global_load_lds_dwordx4 v[0:1], off
	s_cselect_b32 s97, 1, 0
	v_readfirstlane_b32 s101, v193
	s_nop 3
	s_lshr_b32 s101, s101, 6
	s_cmp_lt_u32 s101, 4
	s_cbranch_scc1 .Lpro_skip_11
	s_barrier
.Lpro_skip_11:
	s_waitcnt vmcnt(8)
	s_barrier
	s_cmp_lg_u32 s97, 0
	v_bfe_u32 v0, v193, 4, 2
	v_and_b32_e32 v1, 15, v193
	v_lshlrev_b32_e32 v2, 4, v0
	v_lshl_or_b32 v180, s1, 6, v1
	v_lshl_or_b32 v1, v1, 6, v2
	v_lshlrev_b32_e32 v2, 2, v193
	v_lshl_or_b32 v182, v0, 3, s18
	v_lshlrev_b32_e32 v0, 17, v8
	v_and_b32_e32 v2, 32, v2
	v_and_b32_e32 v0, 0xfffc0000, v0
	v_bitop3_b32 v3, v1, s5, v2 bitop3:0xde
	v_bitop3_b32 v181, v1, s16, v2 bitop3:0xde
	v_lshl_add_u32 v0, v9, 14, v0
	v_and_b32_e32 v1, 1, v8
	v_lshl_or_b32 v0, v1, 6, v0
	v_lshl_add_u32 v144, v10, 1, v0
	v_lshlrev_b32_e32 v0, 17, v11
	v_and_b32_e32 v0, 0xfffc0000, v0
	s_waitcnt vmcnt(6)
	s_cselect_b64 s[14:15], -1, 0
	s_cmp_lg_u64 s[8:9], 0
	v_lshl_add_u32 v0, v12, 14, v0
	v_and_b32_e32 v1, 1, v11
	s_cselect_b64 s[16:17], -1, 0
	v_lshl_or_b32 v0, v1, 6, v0
	s_add_i32 s46, 0, 0x10000
	s_add_i32 s47, 0, 0x14000
	v_mov_b32_e32 v145, v139
	v_lshl_add_u32 v146, v13, 1, v0
	v_mov_b32_e32 v147, v139
	v_mov_b64_e32 v[148:149], 0x200
	v_mov_b64_e32 v[150:151], 0x1ff
	v_add_u32_e32 v183, s46, v181
	v_add_u32_e32 v184, s47, v181
	v_add_u32_e32 v185, 0, v3
	s_barrier
	s_branch .LBB0_1748
